# final RMSNorm phase rewritten with row loads issued one row ahead; act loop head wait hoisted out of the loop
# speedup vs baseline: 1.0133x; 1.0133x over previous
; __device__ __forceinline__ unsigned pack2(float lo, float hi) { unsigned r; asm("v_cvt_pk_bf16_f32 %0, %1, %2" : "=v"(r) : "v"(lo), "v"(hi)); return r; }
; __device__ __forceinline__ float lo16(unsigned w) { return __uint_as_float(w << 16); }
; __device__ __forceinline__ float hi16(unsigned w) { return __uint_as_float(w & 0xffff0000u); }
; __device__ __forceinline__ float gelu_as(float v) {
;     const float av = fabsf(v), t = __builtin_amdgcn_rcpf(av * 0.2316418882f + 1.0f);
;     float q = t * 0.5307027145f + (-0.7265760135f); q = q * t + 0.7107068705f; q = q * t + (-0.142248368f); q = q * t + 0.127414796f; q = q * t;
;     const float e = __builtin_amdgcn_exp2f(v * v * (-0.72134752044f)); const float m = v * (q * e);
;     return v < 0.f ? m : v - m;
; __device__ __forceinline__ void act_phase(int wv, PP P, int L) {
;     ...
;     for (int row = r0; row < r1; row += 4) {
;         u32x4 av[4], bv[4];
; #pragma unroll
;         for (int k = 0; k < 4; ++k) { av[k] = *(const u32x4*)(z2 + (size_t)(row + k) * NUP + c); bv[k] = *(const u32x4*)(z2 + (size_t)(row + k) * NUP + DFF + c); }
; #pragma unroll
;         for (int k = 0; k < 4; ++k) {
;             const u32x4 a0 = av[k], bb = bv[k]; float y[8];
; #pragma unroll
;             for (int q = 0; q < 4; ++q) {
;                 y[2 * q] = bs[2 * q] + w0[2 * q] * lo16(am2[q]) + w1[2 * q] * lo16(am1[q]) + w2[2 * q] * lo16(a0[q]);
;                 y[2 * q + 1] = bs[2 * q + 1] + w0[2 * q + 1] * hi16(am2[q]) + w1[2 * q + 1] * hi16(am1[q]) + w2[2 * q + 1] * hi16(a0[q]);
;             }
;             u32x4 o;
; #pragma unroll
;             for (int q = 0; q < 4; ++q) o[q] = pack2(gelu_as(y[2 * q]) * lo16(bb[q]), gelu_as(y[2 * q + 1]) * hi16(bb[q]));
;             *(u32x4*)(z2 + (size_t)(row + k) * NUP + DFF + c) = o;
;             am2 = am1; am1 = a0;
.LBB0_857:
	s_or_b64 exec, exec, s[10:11]
	s_waitcnt vmcnt(4)
	v_mov_b32_e32 v37, v19
	v_add_u32_e32 v2, 0x5c, v36
	s_waitcnt vmcnt(2)
	v_mov_b32_e32 v72, v26
	v_mov_b32_e32 v75, v19
	v_mov_b32_e32 v19, v26
	v_mov_b32_e32 v26, v37
	v_add_u32_e32 v120, -4, v36
	v_mad_i64_i32 v[36:37], s[10:11], v36, s51, v[0:1]
	v_mov_b32_e32 v38, v17
	v_mov_b32_e32 v39, v15
	v_mov_b32_e32 v40, v13
	v_lshl_add_u64 v[36:37], s[4:5], 0, v[36:37]
	s_mov_b64 s[4:5], 0x8402c00
	v_mov_b32_e32 v73, v18
	v_mov_b32_e32 v74, v27
	v_mov_b32_e32 v76, v24
	v_mov_b32_e32 v77, v16
	v_mov_b32_e32 v78, v25
	v_mov_b32_e32 v79, v17
	v_mov_b32_e32 v80, v22
	v_mov_b32_e32 v81, v14
	v_mov_b32_e32 v82, v23
	v_mov_b32_e32 v83, v15
	v_mov_b32_e32 v84, v20
	v_mov_b32_e32 v85, v12
	v_mov_b32_e32 v86, v21
	v_mov_b32_e32 v87, v13
	v_mov_b32_e32 v17, v24
	v_mov_b32_e32 v24, v38
	v_mov_b32_e32 v15, v22
	v_mov_b32_e32 v22, v39
	v_mov_b32_e32 v13, v20
	v_mov_b32_e32 v20, v40
	v_lshl_add_u64 v[88:89], v[36:37], 0, s[4:5]
	s_mov_b64 s[10:11], 0
	s_waitcnt vmcnt(0)
.LBB0_858:
	v_add_co_u32_e32 v36, vcc, 0xffffe000, v88
	v_lshlrev_b32_e32 v99, 16, v48
	v_addc_co_u32_e32 v37, vcc, -1, v89, vcc
	global_load_dwordx4 v[108:111], v[36:37], off offset:-3072
	global_load_dwordx4 v[68:71], v[88:89], off
	v_and_b32_e32 v107, 0xffff0000, v48
	v_and_b32_e32 v127, 0xffff0000, v44
	v_lshlrev_b32_e32 v126, 16, v44
	v_pk_fma_f32 v[126:127], v[8:9], v[126:127], v[32:33]
	v_add_u32_e32 v36, 5, v120
	v_mov_b64_e32 v[40:41], s[8:9]
	v_mad_i64_i32 v[36:37], s[4:5], v36, s51, v[40:41]
	v_lshl_add_u64 v[36:37], v[36:37], 0, v[0:1]
	v_add_co_u32_e32 v94, vcc, s66, v36
	global_load_dwordx4 v[60:63], v[36:37], off
	s_nop 0
	v_addc_co_u32_e32 v95, vcc, 0, v37, vcc
	global_load_dwordx4 v[64:67], v[94:95], off offset:3072
	v_add_u32_e32 v36, 6, v120
	v_mad_i64_i32 v[36:37], s[4:5], v36, s51, v[40:41]
	v_lshl_add_u64 v[42:43], v[36:37], 0, v[0:1]
	v_add_co_u32_e32 v92, vcc, s66, v42
	global_load_dwordx4 v[36:39], v[42:43], off
	s_nop 0
	v_addc_co_u32_e32 v93, vcc, 0, v43, vcc
	global_load_dwordx4 v[56:59], v[92:93], off offset:3072
	v_add_u32_e32 v42, 7, v120
	v_mad_i64_i32 v[40:41], s[4:5], v42, s51, v[40:41]
	v_lshl_add_u64 v[52:53], v[40:41], 0, v[0:1]
	v_add_co_u32_e32 v90, vcc, s66, v52
	v_lshlrev_b32_e32 v101, 16, v49
	s_nop 0
	v_addc_co_u32_e32 v91, vcc, 0, v53, vcc
	v_and_b32_e32 v105, 0xffff0000, v49
	v_lshlrev_b32_e32 v97, 16, v50
	v_and_b32_e32 v103, 0xffff0000, v50
	v_lshlrev_b32_e32 v49, 16, v51
	v_and_b32_e32 v51, 0xffff0000, v51
	global_load_dwordx4 v[40:43], v[52:53], off
	v_mov_b32_e32 v132, v49
	global_load_dwordx4 v[52:55], v[90:91], off offset:3072
	v_mov_b32_e32 v133, v51
	v_pk_fma_f32 v[132:133], v[6:7], v[132:133], v[30:31]
	v_add_u32_e32 v120, 4, v120
	s_waitcnt vmcnt(7)
	v_lshlrev_b32_e32 v98, 16, v108
	v_and_b32_e32 v106, 0xffff0000, v108
	v_pk_mul_f32 v[122:123], v[84:85], v[98:99]
	v_pk_mul_f32 v[124:125], v[86:87], v[106:107]
	v_mov_b32_e32 v128, v123
	v_mov_b32_e32 v129, v125
	v_pk_add_f32 v[126:127], v[128:129], v[126:127]
	v_mov_b32_e32 v123, v124
	v_pk_add_f32 v[122:123], v[122:123], v[126:127]
	s_waitcnt vmcnt(6)
	v_lshlrev_b32_e32 v121, 16, v68
	v_fma_f32 v44, |v122|, s54, 1.0
	v_rcp_f32_e32 v44, v44
	v_cmp_gt_f32_e64 s[4:5], 0, v122
	v_lshlrev_b32_e32 v100, 16, v109
	v_and_b32_e32 v104, 0xffff0000, v109
	v_fmamk_f32 v124, v44, 0x3f07dc22, v225
	v_fmaak_f32 v124, v44, v124, 0x3f35f0e3
	v_fmaak_f32 v124, v44, v124, 0xbe11a98e
	v_fmaak_f32 v124, v44, v124, 0x3e027906
	v_mul_f32_e32 v44, v44, v124
	v_pk_mul_f32 v[124:125], v[122:123], v[122:123]
	v_cmp_gt_f32_e32 vcc, 0, v123
	v_mul_f32_e32 v124, 0xbf38aa3b, v124
	v_exp_f32_e32 v124, v124
	v_pk_mul_f32 v[116:117], v[80:81], v[100:101]
	v_pk_mul_f32 v[118:119], v[82:83], v[104:105]
	v_and_b32_e32 v68, 0xffff0000, v68
	v_mul_f32_e32 v44, v124, v44
	v_mul_f32_e32 v124, v122, v44
	v_fma_f32 v44, -v122, v44, v122
	v_cndmask_b32_e64 v44, v44, v124, s[4:5]
	v_mul_f32_e32 v44, v44, v121
	v_fma_f32 v121, |v123|, s54, 1.0
	v_rcp_f32_e32 v121, v121
	v_mov_b32_e32 v124, v117
	v_mov_b32_e32 v117, v118
	v_lshlrev_b32_e32 v96, 16, v110
	v_fmamk_f32 v122, v121, 0x3f07dc22, v225
	v_fmaak_f32 v122, v121, v122, 0x3f35f0e3
	v_fmaak_f32 v122, v121, v122, 0xbe11a98e
	v_fmaak_f32 v122, v121, v122, 0x3e027906
	v_mul_f32_e32 v121, v121, v122
	v_mul_f32_e32 v122, 0xbf38aa3b, v125
	v_exp_f32_e32 v122, v122
	v_mov_b32_e32 v125, v119
	v_and_b32_e32 v102, 0xffff0000, v110
	v_pk_mul_f32 v[112:113], v[76:77], v[96:97]
	v_mul_f32_e32 v121, v122, v121
	v_mul_f32_e32 v122, v123, v121
	v_fma_f32 v121, -v123, v121, v123
	v_cndmask_b32_e32 v121, v121, v122, vcc
	v_and_b32_e32 v123, 0xffff0000, v45
	v_lshlrev_b32_e32 v122, 16, v45
	v_pk_fma_f32 v[122:123], v[10:11], v[122:123], v[34:35]
	v_mul_f32_e32 v68, v121, v68
	v_pk_add_f32 v[122:123], v[124:125], v[122:123]
	v_cvt_pk_bf16_f32 v44, v44, v68
	v_lshlrev_b32_e32 v68, 16, v69
	v_pk_add_f32 v[116:117], v[116:117], v[122:123]
	v_and_b32_e32 v69, 0xffff0000, v69
	v_fma_f32 v45, |v116|, s54, 1.0
	v_rcp_f32_e32 v45, v45
	v_cmp_gt_f32_e64 s[4:5], 0, v116
	v_cmp_gt_f32_e32 vcc, 0, v117
	v_pk_mul_f32 v[114:115], v[78:79], v[102:103]
	v_fmamk_f32 v118, v45, 0x3f07dc22, v225
	v_fmaak_f32 v118, v45, v118, 0x3f35f0e3
	v_fmaak_f32 v118, v45, v118, 0xbe11a98e
	v_fmaak_f32 v118, v45, v118, 0x3e027906
	v_mul_f32_e32 v45, v45, v118
	v_pk_mul_f32 v[118:119], v[116:117], v[116:117]
	v_lshlrev_b32_e32 v48, 16, v111
	v_mul_f32_e32 v118, 0xbf38aa3b, v118
	v_exp_f32_e32 v118, v118
	v_and_b32_e32 v50, 0xffff0000, v111
	v_pk_mul_f32 v[108:109], v[72:73], v[48:49]
	v_pk_mul_f32 v[110:111], v[74:75], v[50:51]
	v_mul_f32_e32 v45, v118, v45
	v_mul_f32_e32 v118, v116, v45
	v_fma_f32 v45, -v116, v45, v116
	v_cndmask_b32_e64 v45, v45, v118, s[4:5]
	v_mul_f32_e32 v45, v45, v68
	v_fma_f32 v68, |v117|, s54, 1.0
	v_rcp_f32_e32 v68, v68
	v_lshlrev_b32_e32 v118, 16, v70
	s_waitcnt vmcnt(4)
; __device__ __forceinline__ unsigned pack2(float lo, float hi) { unsigned r; asm("v_cvt_pk_bf16_f32 %0, %1, %2" : "=v"(r) : "v"(lo), "v"(hi)); return r; }
; __device__ __forceinline__ float lo16(unsigned w) { return __uint_as_float(w << 16); }
; __device__ __forceinline__ float hi16(unsigned w) { return __uint_as_float(w & 0xffff0000u); }
; __device__ __forceinline__ float gelu_as(float v) {
;     const float av = fabsf(v), t = __builtin_amdgcn_rcpf(av * 0.2316418882f + 1.0f);
;     float q = t * 0.5307027145f + (-0.7265760135f); q = q * t + 0.7107068705f; q = q * t + (-0.142248368f); q = q * t + 0.127414796f; q = q * t;
;     const float e = __builtin_amdgcn_exp2f(v * v * (-0.72134752044f)); const float m = v * (q * e);
;     return v < 0.f ? m : v - m;
; __device__ __forceinline__ void act_phase(int wv, PP P, int L) {
;     ...
;         for (int k = 0; k < 4; ++k) {
;             const u32x4 a0 = av[k], bb = bv[k]; float y[8];
; #pragma unroll
;             for (int q = 0; q < 4; ++q) {
;                 y[2 * q] = bs[2 * q] + w0[2 * q] * lo16(am2[q]) + w1[2 * q] * lo16(am1[q]) + w2[2 * q] * lo16(a0[q]);
;                 y[2 * q + 1] = bs[2 * q + 1] + w0[2 * q + 1] * hi16(am2[q]) + w1[2 * q + 1] * hi16(am1[q]) + w2[2 * q + 1] * hi16(a0[q]);
;             }
;             u32x4 o;
; #pragma unroll
;             for (int q = 0; q < 4; ++q) o[q] = pack2(gelu_as(y[2 * q]) * lo16(bb[q]), gelu_as(y[2 * q + 1]) * hi16(bb[q]));
;             *(u32x4*)(z2 + (size_t)(row + k) * NUP + DFF + c) = o;
;             am2 = am1; am1 = a0;
	v_lshlrev_b32_e32 v121, 16, v66
	v_and_b32_e32 v128, 0xffff0000, v66
	v_fmamk_f32 v116, v68, 0x3f07dc22, v225
	v_fmaak_f32 v116, v68, v116, 0x3f35f0e3
	v_fmaak_f32 v116, v68, v116, 0xbe11a98e
	v_fmaak_f32 v116, v68, v116, 0x3e027906
	v_mul_f32_e32 v68, v68, v116
	v_mul_f32_e32 v116, 0xbf38aa3b, v119
	v_exp_f32_e32 v116, v116
	v_lshlrev_b32_e32 v136, 16, v67
	v_and_b32_e32 v137, 0xffff0000, v67
	v_mov_b32_e32 v66, v106
	v_mul_f32_e32 v68, v116, v68
	v_mul_f32_e32 v116, v117, v68
	v_fma_f32 v68, -v117, v68, v117
	v_cndmask_b32_e32 v68, v68, v116, vcc
	v_mul_f32_e32 v68, v68, v69
	v_cvt_pk_bf16_f32 v45, v45, v68
	v_and_b32_e32 v69, 0xffff0000, v46
	v_lshlrev_b32_e32 v68, 16, v46
	v_pk_fma_f32 v[68:69], v[4:5], v[68:69], v[28:29]
	v_mov_b32_e32 v116, v113
	v_mov_b32_e32 v117, v115
	v_pk_add_f32 v[68:69], v[116:117], v[68:69]
	v_mov_b32_e32 v113, v114
	v_pk_add_f32 v[68:69], v[112:113], v[68:69]
	s_nop 0
	v_fma_f32 v46, |v68|, s54, 1.0
	v_rcp_f32_e32 v46, v46
	v_cmp_gt_f32_e64 s[4:5], 0, v68
	v_cmp_gt_f32_e32 vcc, 0, v69
	v_fmamk_f32 v112, v46, 0x3f07dc22, v225
	v_fmaak_f32 v112, v46, v112, 0x3f35f0e3
	v_fmaak_f32 v112, v46, v112, 0xbe11a98e
	v_fmaak_f32 v112, v46, v112, 0x3e027906
	v_mul_f32_e32 v46, v46, v112
	v_pk_mul_f32 v[112:113], v[68:69], v[68:69]
	s_nop 0
	v_mul_f32_e32 v112, 0xbf38aa3b, v112
	v_exp_f32_e32 v112, v112
	s_nop 0
	v_mul_f32_e32 v46, v112, v46
	v_mul_f32_e32 v112, v68, v46
	v_fma_f32 v46, -v68, v46, v68
	v_fma_f32 v68, |v69|, s54, 1.0
	v_rcp_f32_e32 v68, v68
	v_cndmask_b32_e64 v46, v46, v112, s[4:5]
	v_mul_f32_e32 v46, v46, v118
	v_fmamk_f32 v112, v68, 0x3f07dc22, v225
	v_fmaak_f32 v112, v68, v112, 0x3f35f0e3
	v_fmaak_f32 v112, v68, v112, 0xbe11a98e
	v_fmaak_f32 v112, v68, v112, 0x3e027906
	v_mul_f32_e32 v68, v68, v112
	v_mul_f32_e32 v112, 0xbf38aa3b, v113
	v_exp_f32_e32 v112, v112
	v_mov_b32_e32 v113, v111
	v_lshlrev_b32_e32 v111, 16, v65
	v_mul_f32_e32 v68, v112, v68
	v_mul_f32_e32 v112, v69, v68
	v_fma_f32 v68, -v69, v68, v69
	v_cndmask_b32_e32 v68, v68, v112, vcc
	v_and_b32_e32 v69, 0xffff0000, v70
	v_mul_f32_e32 v68, v68, v69
	v_cvt_pk_bf16_f32 v46, v46, v68
	v_and_b32_e32 v69, 0xffff0000, v47
	v_lshlrev_b32_e32 v68, 16, v47
	v_pk_fma_f32 v[68:69], v[6:7], v[68:69], v[30:31]
	v_mov_b32_e32 v112, v109
	v_pk_add_f32 v[68:69], v[112:113], v[68:69]
	v_mov_b32_e32 v109, v110
	v_pk_add_f32 v[68:69], v[108:109], v[68:69]
	v_lshlrev_b32_e32 v70, 16, v71
	v_fma_f32 v47, |v68|, s54, 1.0
	v_rcp_f32_e32 v47, v47
	v_cmp_gt_f32_e64 s[4:5], 0, v68
	v_cmp_gt_f32_e32 vcc, 0, v69
	v_and_b32_e32 v112, 0xffff0000, v65
	v_fmamk_f32 v108, v47, 0x3f07dc22, v225
	v_fmaak_f32 v108, v47, v108, 0x3f35f0e3
	v_fmaak_f32 v108, v47, v108, 0xbe11a98e
	v_fmaak_f32 v108, v47, v108, 0x3e027906
	v_mul_f32_e32 v47, v47, v108
	v_pk_mul_f32 v[108:109], v[68:69], v[68:69]
	v_mov_b32_e32 v113, v103
	v_mul_f32_e32 v108, 0xbf38aa3b, v108
	v_exp_f32_e32 v108, v108
	s_nop 0
	v_mul_f32_e32 v47, v108, v47
	v_mul_f32_e32 v108, v68, v47
	v_fma_f32 v47, -v68, v47, v68
	v_fma_f32 v68, |v69|, s54, 1.0
	v_rcp_f32_e32 v68, v68
	v_cndmask_b32_e64 v47, v47, v108, s[4:5]
	v_mul_f32_e32 v47, v47, v70
	v_lshlrev_b32_e32 v108, 16, v64
	v_fmamk_f32 v70, v68, 0x3f07dc22, v225
	v_fmaak_f32 v70, v68, v70, 0x3f35f0e3
	v_fmaak_f32 v70, v68, v70, 0xbe11a98e
	v_fmaak_f32 v70, v68, v70, 0x3e027906
	v_mul_f32_e32 v68, v68, v70
	v_mul_f32_e32 v70, 0xbf38aa3b, v109
	v_exp_f32_e32 v70, v70
	v_and_b32_e32 v109, 0xffff0000, v64
	v_mul_f32_e32 v68, v70, v68
	v_mul_f32_e32 v70, v69, v68
	v_fma_f32 v68, -v69, v68, v69
	v_cndmask_b32_e32 v68, v68, v70, vcc
	v_and_b32_e32 v69, 0xffff0000, v71
	v_mul_f32_e32 v68, v68, v69
	v_cvt_pk_bf16_f32 v47, v47, v68
	global_store_dwordx4 v[88:89], v[44:47], off
	v_mov_b32_e32 v68, v99
	v_mov_b32_e32 v69, v107
	v_lshlrev_b32_e32 v44, 16, v60
	v_mov_b32_e32 v46, v98
	v_mov_b32_e32 v47, v44
	v_pk_mul_f32 v[64:65], v[12:13], v[46:47]
	v_and_b32_e32 v46, 0xffff0000, v60
	v_mov_b32_e32 v67, v46
	v_pk_mul_f32 v[66:67], v[20:21], v[66:67]
	v_pk_fma_f32 v[68:69], v[8:9], v[68:69], v[32:33]
	v_mov_b32_e32 v70, v64
	v_mov_b32_e32 v71, v66
	v_pk_add_f32 v[68:69], v[68:69], v[70:71]
	v_mov_b32_e32 v66, v65
	v_pk_add_f32 v[64:65], v[68:69], v[66:67]
	v_mov_b32_e32 v70, v101
	v_fma_f32 v60, |v64|, s54, 1.0
	v_rcp_f32_e32 v60, v60
	v_cmp_gt_f32_e64 s[4:5], 0, v64
	v_cmp_gt_f32_e32 vcc, 0, v65
	v_mov_b32_e32 v71, v105
	v_fmamk_f32 v66, v60, 0x3f07dc22, v225
	v_fmaak_f32 v66, v60, v66, 0x3f35f0e3
	v_fmaak_f32 v66, v60, v66, 0xbe11a98e
	v_fmaak_f32 v66, v60, v66, 0x3e027906
	v_mul_f32_e32 v60, v60, v66
	v_pk_mul_f32 v[66:67], v[64:65], v[64:65]
	v_pk_fma_f32 v[70:71], v[10:11], v[70:71], v[34:35]
	v_mul_f32_e32 v66, 0xbf38aa3b, v66
	v_exp_f32_e32 v66, v66
	s_waitcnt vmcnt(4)
; __device__ __forceinline__ unsigned pack2(float lo, float hi) { unsigned r; asm("v_cvt_pk_bf16_f32 %0, %1, %2" : "=v"(r) : "v"(lo), "v"(hi)); return r; }
; __device__ __forceinline__ float lo16(unsigned w) { return __uint_as_float(w << 16); }
; __device__ __forceinline__ float hi16(unsigned w) { return __uint_as_float(w & 0xffff0000u); }
; __device__ __forceinline__ float gelu_as(float v) {
;     const float av = fabsf(v), t = __builtin_amdgcn_rcpf(av * 0.2316418882f + 1.0f);
;     float q = t * 0.5307027145f + (-0.7265760135f); q = q * t + 0.7107068705f; q = q * t + (-0.142248368f); q = q * t + 0.127414796f; q = q * t;
;     const float e = __builtin_amdgcn_exp2f(v * v * (-0.72134752044f)); const float m = v * (q * e);
;     return v < 0.f ? m : v - m;
; __device__ __forceinline__ void act_phase(int wv, PP P, int L) {
;     ...
;         for (int k = 0; k < 4; ++k) {
;             const u32x4 a0 = av[k], bb = bv[k]; float y[8];
; #pragma unroll
;             for (int q = 0; q < 4; ++q) {
;                 y[2 * q] = bs[2 * q] + w0[2 * q] * lo16(am2[q]) + w1[2 * q] * lo16(am1[q]) + w2[2 * q] * lo16(a0[q]);
;                 y[2 * q + 1] = bs[2 * q + 1] + w0[2 * q + 1] * hi16(am2[q]) + w1[2 * q + 1] * hi16(am1[q]) + w2[2 * q + 1] * hi16(a0[q]);
;             }
;             u32x4 o;
; #pragma unroll
;             for (int q = 0; q < 4; ++q) o[q] = pack2(gelu_as(y[2 * q]) * lo16(bb[q]), gelu_as(y[2 * q + 1]) * hi16(bb[q]));
;             *(u32x4*)(z2 + (size_t)(row + k) * NUP + DFF + c) = o;
;             am2 = am1; am1 = a0;
	v_lshlrev_b32_e32 v45, 16, v36
	v_and_b32_e32 v47, 0xffff0000, v36
	v_pk_mul_f32 v[114:115], v[12:13], v[44:45]
	v_mul_f32_e32 v60, v66, v60
	v_mul_f32_e32 v66, v64, v60
	v_fma_f32 v60, -v64, v60, v64
	v_fma_f32 v64, |v65|, s54, 1.0
	v_rcp_f32_e32 v64, v64
	v_cndmask_b32_e64 v60, v60, v66, s[4:5]
	v_mul_f32_e32 v60, v60, v108
	v_pk_mul_f32 v[116:117], v[20:21], v[46:47]
	v_fmamk_f32 v66, v64, 0x3f07dc22, v225
	v_fmaak_f32 v66, v64, v66, 0x3f35f0e3
	v_fmaak_f32 v66, v64, v66, 0xbe11a98e
	v_fmaak_f32 v66, v64, v66, 0x3e027906
	v_mul_f32_e32 v64, v64, v66
	v_mul_f32_e32 v66, 0xbf38aa3b, v67
	v_exp_f32_e32 v66, v66
	v_mov_b32_e32 v99, v106
	v_mov_b32_e32 v101, v104
	v_mul_f32_e32 v64, v66, v64
	v_mul_f32_e32 v66, v65, v64
	v_fma_f32 v64, -v65, v64, v65
	v_cndmask_b32_e32 v64, v64, v66, vcc
	v_mul_f32_e32 v64, v64, v109
	v_cvt_pk_bf16_f32 v110, v60, v64
	v_lshlrev_b32_e32 v64, 16, v61
	v_mov_b32_e32 v66, v100
	v_mov_b32_e32 v67, v64
	v_pk_mul_f32 v[68:69], v[14:15], v[66:67]
	v_and_b32_e32 v66, 0xffff0000, v61
	v_mov_b32_e32 v60, v104
	v_mov_b32_e32 v61, v66
	v_pk_mul_f32 v[60:61], v[22:23], v[60:61]
	v_mov_b32_e32 v108, v68
	v_mov_b32_e32 v109, v60
	v_pk_add_f32 v[70:71], v[70:71], v[108:109]
	v_mov_b32_e32 v60, v69
	v_pk_add_f32 v[60:61], v[70:71], v[60:61]
	v_mov_b32_e32 v108, v102
	v_fma_f32 v68, |v60|, s54, 1.0
	v_rcp_f32_e32 v68, v68
	v_cmp_gt_f32_e64 s[4:5], 0, v60
	v_cmp_gt_f32_e32 vcc, 0, v61
	v_lshlrev_b32_e32 v65, 16, v37
	v_fmamk_f32 v69, v68, 0x3f07dc22, v225
	v_fmaak_f32 v69, v68, v69, 0x3f35f0e3
	v_fmaak_f32 v69, v68, v69, 0xbe11a98e
	v_fmaak_f32 v69, v68, v69, 0x3e027906
	v_mul_f32_e32 v70, v68, v69
	v_pk_mul_f32 v[68:69], v[60:61], v[60:61]
	v_and_b32_e32 v67, 0xffff0000, v37
	v_mul_f32_e32 v68, 0xbf38aa3b, v68
	v_exp_f32_e32 v68, v68
	v_mul_f32_e32 v69, 0xbf38aa3b, v69
	v_exp_f32_e32 v69, v69
	v_pk_mul_f32 v[118:119], v[14:15], v[64:65]
	v_mul_f32_e32 v68, v68, v70
	v_mul_f32_e32 v70, v60, v68
	v_fma_f32 v68, -v60, v68, v60
	v_cndmask_b32_e64 v60, v68, v70, s[4:5]
	v_fma_f32 v68, |v61|, s54, 1.0
	v_rcp_f32_e32 v68, v68
	v_mul_f32_e32 v60, v60, v111
	v_pk_mul_f32 v[122:123], v[22:23], v[66:67]
	v_fmamk_f32 v70, v68, 0x3f07dc22, v225
	v_fmaak_f32 v70, v68, v70, 0x3f35f0e3
	v_fmaak_f32 v70, v68, v70, 0xbe11a98e
	v_fmaak_f32 v70, v68, v70, 0x3e027906
	v_mul_f32_e32 v68, v68, v70
	v_mul_f32_e32 v68, v69, v68
	v_mul_f32_e32 v69, v61, v68
	v_fma_f32 v61, -v61, v68, v61
	v_cndmask_b32_e32 v61, v61, v69, vcc
	v_mul_f32_e32 v61, v61, v112
	v_cvt_pk_bf16_f32 v111, v60, v61
	v_lshlrev_b32_e32 v60, 16, v62
	v_mov_b32_e32 v68, v96
	v_mov_b32_e32 v69, v60
	v_pk_mul_f32 v[70:71], v[16:17], v[68:69]
	v_and_b32_e32 v68, 0xffff0000, v62
	v_mov_b32_e32 v109, v68
	v_pk_mul_f32 v[108:109], v[24:25], v[108:109]
	v_mov_b32_e32 v112, v97
	v_pk_fma_f32 v[112:113], v[4:5], v[112:113], v[28:29]
	v_mov_b32_e32 v126, v70
	v_mov_b32_e32 v127, v108
	v_pk_add_f32 v[112:113], v[112:113], v[126:127]
	v_mov_b32_e32 v108, v71
	v_pk_add_f32 v[70:71], v[112:113], v[108:109]
	v_lshlrev_b32_e32 v61, 16, v38
	v_fma_f32 v62, |v70|, s54, 1.0
	v_rcp_f32_e32 v62, v62
	v_pk_mul_f32 v[108:109], v[70:71], v[70:71]
	v_cmp_gt_f32_e64 s[4:5], 0, v70
	v_cmp_gt_f32_e32 vcc, 0, v71
	v_fmamk_f32 v97, v62, 0x3f07dc22, v225
	v_fmaak_f32 v97, v62, v97, 0x3f35f0e3
	v_fmaak_f32 v97, v62, v97, 0xbe11a98e
	v_fmaak_f32 v97, v62, v97, 0x3e027906
	v_mul_f32_e32 v62, v62, v97
	v_mul_f32_e32 v97, 0xbf38aa3b, v108
	v_exp_f32_e32 v97, v97
	v_mov_b32_e32 v108, v48
	v_and_b32_e32 v69, 0xffff0000, v38
	v_pk_mul_f32 v[124:125], v[16:17], v[60:61]
	v_mul_f32_e32 v62, v97, v62
	v_mul_f32_e32 v97, v70, v62
	v_fma_f32 v62, -v70, v62, v70
	v_fma_f32 v70, |v71|, s54, 1.0
	v_rcp_f32_e32 v70, v70
	v_cndmask_b32_e64 v62, v62, v97, s[4:5]
	v_mul_f32_e32 v62, v62, v121
	v_pk_mul_f32 v[126:127], v[24:25], v[68:69]
	v_fmamk_f32 v97, v70, 0x3f07dc22, v225
	v_fmaak_f32 v97, v70, v97, 0x3f35f0e3
	v_fmaak_f32 v97, v70, v97, 0xbe11a98e
	v_fmaak_f32 v97, v70, v97, 0x3e027906
	v_mul_f32_e32 v70, v70, v97
	v_mul_f32_e32 v97, 0xbf38aa3b, v109
	v_exp_f32_e32 v97, v97
	s_nop 0
	v_mul_f32_e32 v70, v97, v70
	v_mul_f32_e32 v97, v71, v70
	v_fma_f32 v70, -v71, v70, v71
	v_cndmask_b32_e32 v70, v70, v97, vcc
	v_mul_f32_e32 v70, v70, v128
	v_cvt_pk_bf16_f32 v112, v62, v70
	v_lshlrev_b32_e32 v70, 16, v63
	v_mov_b32_e32 v109, v70
	v_pk_mul_f32 v[128:129], v[18:19], v[108:109]
	v_and_b32_e32 v108, 0xffff0000, v63
	v_mov_b32_e32 v62, v50
	v_mov_b32_e32 v63, v108
	v_pk_mul_f32 v[62:63], v[26:27], v[62:63]
	v_mov_b32_e32 v134, v128
	v_mov_b32_e32 v135, v62
	v_pk_add_f32 v[132:133], v[132:133], v[134:135]
	v_mov_b32_e32 v62, v129
	v_pk_add_f32 v[62:63], v[132:133], v[62:63]
	v_lshlrev_b32_e32 v71, 16, v39
	v_fma_f32 v49, |v62|, s54, 1.0
	v_rcp_f32_e32 v49, v49
	v_pk_mul_f32 v[128:129], v[62:63], v[62:63]
	v_cmp_gt_f32_e64 s[4:5], 0, v62
	v_cmp_gt_f32_e32 vcc, 0, v63
	v_fmamk_f32 v51, v49, 0x3f07dc22, v225
	v_fmaak_f32 v51, v49, v51, 0x3f35f0e3
	v_fmaak_f32 v51, v49, v51, 0xbe11a98e
	v_fmaak_f32 v51, v49, v51, 0x3e027906
	v_mul_f32_e32 v49, v49, v51
	v_mul_f32_e32 v51, 0xbf38aa3b, v128
	v_exp_f32_e32 v51, v51
	v_and_b32_e32 v109, 0xffff0000, v39
	v_pk_mul_f32 v[130:131], v[18:19], v[70:71]
	v_mul_f32_e32 v49, v51, v49
	v_mul_f32_e32 v51, v62, v49
	v_fma_f32 v49, -v62, v49, v62
	v_cndmask_b32_e64 v49, v49, v51, s[4:5]
	v_fma_f32 v51, |v63|, s54, 1.0
	v_rcp_f32_e32 v51, v51
	v_mul_f32_e32 v49, v49, v136
	v_fmamk_f32 v62, v51, 0x3f07dc22, v225
	v_fmaak_f32 v62, v51, v62, 0x3f35f0e3
	v_fmaak_f32 v62, v51, v62, 0xbe11a98e
	v_fmaak_f32 v62, v51, v62, 0x3e027906
	v_mul_f32_e32 v51, v51, v62
	v_mul_f32_e32 v62, 0xbf38aa3b, v129
	v_exp_f32_e32 v62, v62
	s_nop 0
	v_mul_f32_e32 v51, v62, v51
	v_mul_f32_e32 v62, v63, v51
	v_fma_f32 v51, -v63, v51, v63
	v_cndmask_b32_e32 v51, v51, v62, vcc
	v_mul_f32_e32 v51, v51, v137
	v_cvt_pk_bf16_f32 v113, v49, v51
	global_store_dwordx4 v[94:95], v[110:113], off offset:3072
	v_pk_fma_f32 v[94:95], v[8:9], v[98:99], v[32:33]
	v_mov_b32_e32 v98, v114
	v_mov_b32_e32 v99, v116
	v_pk_add_f32 v[94:95], v[94:95], v[98:99]
	v_mov_b32_e32 v116, v115
	v_pk_add_f32 v[94:95], v[94:95], v[116:117]
	s_waitcnt vmcnt(4)
; __device__ __forceinline__ unsigned pack2(float lo, float hi) { unsigned r; asm("v_cvt_pk_bf16_f32 %0, %1, %2" : "=v"(r) : "v"(lo), "v"(hi)); return r; }
; __device__ __forceinline__ float lo16(unsigned w) { return __uint_as_float(w << 16); }
; __device__ __forceinline__ float hi16(unsigned w) { return __uint_as_float(w & 0xffff0000u); }
; __device__ __forceinline__ void act_phase(int wv, PP P, int L) {
;     ...
;             const u32x4 a0 = av[k], bb = bv[k]; float y[8];
; #pragma unroll
;             for (int q = 0; q < 4; ++q) {
;                 y[2 * q] = bs[2 * q] + w0[2 * q] * lo16(am2[q]) + w1[2 * q] * lo16(am1[q]) + w2[2 * q] * lo16(a0[q]);
;                 y[2 * q + 1] = bs[2 * q + 1] + w0[2 * q + 1] * hi16(am2[q]) + w1[2 * q + 1] * hi16(am1[q]) + w2[2 * q + 1] * hi16(a0[q]);
;             }
;             u32x4 o;
; #pragma unroll
;             for (int q = 0; q < 4; ++q) o[q] = pack2(gelu_as(y[2 * q]) * lo16(bb[q]), gelu_as(y[2 * q + 1]) * hi16(bb[q]));
;             *(u32x4*)(z2 + (size_t)(row + k) * NUP + DFF + c) = o;
	v_lshlrev_b32_e32 v49, 16, v56
	v_fma_f32 v51, |v94|, s54, 1.0
	v_rcp_f32_e32 v51, v51
	v_pk_mul_f32 v[98:99], v[94:95], v[94:95]
	v_cmp_gt_f32_e64 s[4:5], 0, v94
	v_cmp_gt_f32_e32 vcc, 0, v95
	v_fmamk_f32 v97, v51, 0x3f07dc22, v225
	v_fmaak_f32 v97, v51, v97, 0x3f35f0e3
	v_fmaak_f32 v97, v51, v97, 0xbe11a98e
	v_fmaak_f32 v97, v51, v97, 0x3e027906
	v_mul_f32_e32 v51, v51, v97
	v_mul_f32_e32 v97, 0xbf38aa3b, v98
	v_exp_f32_e32 v97, v97
	v_mov_b32_e32 v98, v118
	v_and_b32_e32 v56, 0xffff0000, v56
	v_pk_mul_f32 v[62:63], v[26:27], v[108:109]
	v_mul_f32_e32 v51, v97, v51
	v_mul_f32_e32 v97, v94, v51
	v_fma_f32 v51, -v94, v51, v94
	v_cndmask_b32_e64 v51, v51, v97, s[4:5]
	v_mul_f32_e32 v49, v51, v49
	v_fma_f32 v51, |v95|, s54, 1.0
	v_rcp_f32_e32 v51, v51
	s_nop 0
	v_fmamk_f32 v94, v51, 0x3f07dc22, v225
	v_fmaak_f32 v94, v51, v94, 0x3f35f0e3
	v_fmaak_f32 v94, v51, v94, 0xbe11a98e
	v_fmaak_f32 v94, v51, v94, 0x3e027906
	v_mul_f32_e32 v51, v51, v94
	v_mul_f32_e32 v94, 0xbf38aa3b, v99
	v_exp_f32_e32 v94, v94
	v_mov_b32_e32 v99, v122
	v_mov_b32_e32 v122, v119
	v_mul_f32_e32 v51, v94, v51
	v_mul_f32_e32 v94, v95, v51
	v_fma_f32 v51, -v95, v51, v95
	v_cndmask_b32_e32 v51, v51, v94, vcc
	v_pk_fma_f32 v[94:95], v[10:11], v[100:101], v[34:35]
	v_mul_f32_e32 v51, v51, v56
	v_pk_add_f32 v[94:95], v[94:95], v[98:99]
	v_cvt_pk_bf16_f32 v56, v49, v51
	v_lshlrev_b32_e32 v49, 16, v57
	v_pk_add_f32 v[94:95], v[94:95], v[122:123]
	v_and_b32_e32 v57, 0xffff0000, v57
	v_fma_f32 v51, |v94|, s54, 1.0
	v_rcp_f32_e32 v51, v51
	v_pk_mul_f32 v[98:99], v[94:95], v[94:95]
	v_cmp_gt_f32_e64 s[4:5], 0, v94
	v_cmp_gt_f32_e32 vcc, 0, v95
	v_fmamk_f32 v97, v51, 0x3f07dc22, v225
	v_fmaak_f32 v97, v51, v97, 0x3f35f0e3
	v_fmaak_f32 v97, v51, v97, 0xbe11a98e
	v_fmaak_f32 v97, v51, v97, 0x3e027906
	v_mul_f32_e32 v51, v51, v97
	v_mul_f32_e32 v97, 0xbf38aa3b, v98
	v_exp_f32_e32 v97, v97
	s_nop 0
	v_mul_f32_e32 v51, v97, v51
	v_mul_f32_e32 v97, v94, v51
	v_fma_f32 v51, -v94, v51, v94
	v_cndmask_b32_e64 v51, v51, v97, s[4:5]
	v_mul_f32_e32 v49, v51, v49
	v_fma_f32 v51, |v95|, s54, 1.0
	v_rcp_f32_e32 v51, v51
	v_mov_b32_e32 v97, v102
	v_fmamk_f32 v94, v51, 0x3f07dc22, v225
	v_fmaak_f32 v94, v51, v94, 0x3f35f0e3
	v_fmaak_f32 v94, v51, v94, 0xbe11a98e
	v_fmaak_f32 v94, v51, v94, 0x3e027906
	v_mul_f32_e32 v51, v51, v94
	v_mul_f32_e32 v94, 0xbf38aa3b, v99
	v_exp_f32_e32 v94, v94
	s_nop 0
	v_mul_f32_e32 v51, v94, v51
	v_mul_f32_e32 v94, v95, v51
	v_fma_f32 v51, -v95, v51, v95
	v_cndmask_b32_e32 v51, v51, v94, vcc
	v_pk_fma_f32 v[94:95], v[4:5], v[96:97], v[28:29]
	v_mov_b32_e32 v96, v124
	v_mov_b32_e32 v97, v126
	v_pk_add_f32 v[94:95], v[94:95], v[96:97]
	v_mov_b32_e32 v126, v125
	v_mul_f32_e32 v51, v51, v57
	v_pk_add_f32 v[94:95], v[94:95], v[126:127]
	v_cvt_pk_bf16_f32 v57, v49, v51
	v_lshlrev_b32_e32 v49, 16, v58
	v_fma_f32 v51, |v94|, s54, 1.0
	v_rcp_f32_e32 v51, v51
	v_cmp_gt_f32_e64 s[4:5], 0, v94
	v_cmp_gt_f32_e32 vcc, 0, v95
	v_and_b32_e32 v58, 0xffff0000, v58
	v_fmamk_f32 v96, v51, 0x3f07dc22, v225
	v_fmaak_f32 v96, v51, v96, 0x3f35f0e3
	v_fmaak_f32 v96, v51, v96, 0xbe11a98e
	v_fmaak_f32 v96, v51, v96, 0x3e027906
	v_mul_f32_e32 v51, v51, v96
	v_pk_mul_f32 v[96:97], v[94:95], v[94:95]
	s_nop 0
	v_mul_f32_e32 v96, 0xbf38aa3b, v96
	v_exp_f32_e32 v96, v96
	s_nop 0
	v_mul_f32_e32 v51, v96, v51
	v_mul_f32_e32 v96, v94, v51
	v_fma_f32 v51, -v94, v51, v94
	v_cndmask_b32_e64 v51, v51, v96, s[4:5]
	v_mul_f32_e32 v49, v51, v49
	v_fma_f32 v51, |v95|, s54, 1.0
	v_rcp_f32_e32 v51, v51
	v_mov_b32_e32 v96, v109
	v_fmamk_f32 v94, v51, 0x3f07dc22, v225
	v_fmaak_f32 v94, v51, v94, 0x3f35f0e3
	v_fmaak_f32 v94, v51, v94, 0xbe11a98e
	v_fmaak_f32 v94, v51, v94, 0x3e027906
	v_mul_f32_e32 v51, v51, v94
	v_mul_f32_e32 v94, 0xbf38aa3b, v97
	v_exp_f32_e32 v94, v94
	s_waitcnt vmcnt(3)
	v_and_b32_e32 v97, 0xffff0000, v43
	v_pk_mul_f32 v[96:97], v[26:27], v[96:97]
	v_mul_f32_e32 v51, v94, v51
	v_mul_f32_e32 v94, v95, v51
	v_fma_f32 v51, -v95, v51, v95
	v_cndmask_b32_e32 v51, v51, v94, vcc
	v_mul_f32_e32 v51, v51, v58
	v_cvt_pk_bf16_f32 v58, v49, v51
	v_mov_b32_e32 v49, v50
	v_pk_fma_f32 v[48:49], v[6:7], v[48:49], v[30:31]
	v_mov_b32_e32 v50, v130
	v_mov_b32_e32 v51, v62
	v_pk_add_f32 v[48:49], v[48:49], v[50:51]
	v_mov_b32_e32 v62, v131
	v_pk_add_f32 v[48:49], v[48:49], v[62:63]
	v_lshlrev_b32_e32 v94, 16, v59
	v_fma_f32 v50, |v48|, s54, 1.0
	v_rcp_f32_e32 v50, v50
	v_cmp_gt_f32_e64 s[4:5], 0, v48
	v_cmp_gt_f32_e32 vcc, 0, v49
	v_lshlrev_b32_e32 v63, 16, v42
	v_fmamk_f32 v51, v50, 0x3f07dc22, v225
	v_fmaak_f32 v51, v50, v51, 0x3f35f0e3
	v_fmaak_f32 v51, v50, v51, 0xbe11a98e
	v_fmaak_f32 v51, v50, v51, 0x3e027906
	v_mul_f32_e32 v62, v50, v51
	v_pk_mul_f32 v[50:51], v[48:49], v[48:49]
	v_lshlrev_b32_e32 v95, 16, v43
	v_mul_f32_e32 v50, 0xbf38aa3b, v50
	v_exp_f32_e32 v50, v50
	v_mul_f32_e32 v51, 0xbf38aa3b, v51
	v_exp_f32_e32 v51, v51
	v_mul_f32_e32 v50, v50, v62
	v_mul_f32_e32 v62, v48, v50
	v_fma_f32 v50, -v48, v50, v48
	v_cndmask_b32_e64 v48, v50, v62, s[4:5]
	v_fma_f32 v50, |v49|, s54, 1.0
	v_rcp_f32_e32 v50, v50
	v_mul_f32_e32 v48, v48, v94
	v_mov_b32_e32 v94, v71
	v_pk_mul_f32 v[94:95], v[18:19], v[94:95]
	v_fmamk_f32 v62, v50, 0x3f07dc22, v225
	v_fmaak_f32 v62, v50, v62, 0x3f35f0e3
	v_fmaak_f32 v62, v50, v62, 0xbe11a98e
	v_fmaak_f32 v62, v50, v62, 0x3e027906
	v_mul_f32_e32 v50, v50, v62
	v_mul_f32_e32 v50, v51, v50
	v_mul_f32_e32 v51, v49, v50
	v_fma_f32 v49, -v49, v50, v49
	v_cndmask_b32_e32 v49, v49, v51, vcc
	v_and_b32_e32 v50, 0xffff0000, v59
	v_mul_f32_e32 v49, v49, v50
	v_cvt_pk_bf16_f32 v59, v48, v49
	v_lshlrev_b32_e32 v49, 16, v40
	v_mov_b32_e32 v48, v45
	v_and_b32_e32 v51, 0xffff0000, v40
; __device__ __forceinline__ unsigned pack2(float lo, float hi) { unsigned r; asm("v_cvt_pk_bf16_f32 %0, %1, %2" : "=v"(r) : "v"(lo), "v"(hi)); return r; }
; __device__ __forceinline__ float lo16(unsigned w) { return __uint_as_float(w << 16); }
; __device__ __forceinline__ float hi16(unsigned w) { return __uint_as_float(w & 0xffff0000u); }
; __device__ __forceinline__ void act_phase(int wv, PP P, int L) {
;     ...
;             const u32x4 a0 = av[k], bb = bv[k]; float y[8];
; #pragma unroll
;             for (int q = 0; q < 4; ++q) {
;                 y[2 * q] = bs[2 * q] + w0[2 * q] * lo16(am2[q]) + w1[2 * q] * lo16(am1[q]) + w2[2 * q] * lo16(a0[q]);
;                 y[2 * q + 1] = bs[2 * q + 1] + w0[2 * q + 1] * hi16(am2[q]) + w1[2 * q + 1] * hi16(am1[q]) + w2[2 * q + 1] * hi16(a0[q]);
;             }
;             u32x4 o;
; #pragma unroll
;             for (int q = 0; q < 4; ++q) o[q] = pack2(gelu_as(y[2 * q]) * lo16(bb[q]), gelu_as(y[2 * q + 1]) * hi16(bb[q]));
;             *(u32x4*)(z2 + (size_t)(row + k) * NUP + DFF + c) = o;
;             am2 = am1; am1 = a0;
;         }
;     }
	v_mov_b32_e32 v50, v47
	v_pk_mul_f32 v[48:49], v[12:13], v[48:49]
	v_pk_mul_f32 v[50:51], v[20:21], v[50:51]
	v_mov_b32_e32 v45, v46
	v_pk_fma_f32 v[44:45], v[8:9], v[44:45], v[32:33]
	v_mov_b32_e32 v46, v48
	v_mov_b32_e32 v47, v50
	v_pk_add_f32 v[44:45], v[44:45], v[46:47]
	v_mov_b32_e32 v50, v49
	v_pk_add_f32 v[44:45], v[44:45], v[50:51]
	global_store_dwordx4 v[92:93], v[56:59], off offset:3072
	v_fma_f32 v46, |v44|, s54, 1.0
	v_rcp_f32_e32 v46, v46
	v_cmp_gt_f32_e64 s[4:5], 0, v44
	v_lshlrev_b32_e32 v57, 16, v41
	v_mov_b32_e32 v56, v65
	v_fmamk_f32 v47, v46, 0x3f07dc22, v225
	v_fmaak_f32 v47, v46, v47, 0x3f35f0e3
	v_fmaak_f32 v47, v46, v47, 0xbe11a98e
	v_fmaak_f32 v47, v46, v47, 0x3e027906
	v_mul_f32_e32 v48, v46, v47
	v_pk_mul_f32 v[46:47], v[44:45], v[44:45]
	v_and_b32_e32 v59, 0xffff0000, v41
	v_mul_f32_e32 v46, 0xbf38aa3b, v46
	v_exp_f32_e32 v46, v46
	v_mul_f32_e32 v47, 0xbf38aa3b, v47
	v_exp_f32_e32 v47, v47
	v_mov_b32_e32 v58, v67
	v_mul_f32_e32 v46, v46, v48
	v_mul_f32_e32 v48, v44, v46
	v_fma_f32 v46, -v44, v46, v44
	v_cndmask_b32_e64 v44, v46, v48, s[4:5]
	v_fma_f32 v46, |v45|, s54, 1.0
	v_rcp_f32_e32 v46, v46
	v_cmp_gt_f32_e32 vcc, 0, v45
	v_pk_mul_f32 v[56:57], v[14:15], v[56:57]
	v_pk_mul_f32 v[58:59], v[22:23], v[58:59]
	v_fmamk_f32 v48, v46, 0x3f07dc22, v225
	v_fmaak_f32 v48, v46, v48, 0x3f35f0e3
	v_fmaak_f32 v48, v46, v48, 0xbe11a98e
	v_fmaak_f32 v48, v46, v48, 0x3e027906
	v_mul_f32_e32 v46, v46, v48
	v_mul_f32_e32 v46, v47, v46
	v_mul_f32_e32 v47, v45, v46
	v_fma_f32 v45, -v45, v46, v45
	v_cndmask_b32_e32 v45, v45, v47, vcc
	s_waitcnt vmcnt(3)
	v_and_b32_e32 v46, 0xffff0000, v52
	v_mov_b32_e32 v65, v66
	v_mul_f32_e32 v45, v45, v46
	v_pk_fma_f32 v[46:47], v[10:11], v[64:65], v[34:35]
	v_mov_b32_e32 v48, v56
	v_mov_b32_e32 v49, v58
	v_pk_add_f32 v[46:47], v[46:47], v[48:49]
	v_mov_b32_e32 v58, v57
	v_pk_add_f32 v[46:47], v[46:47], v[58:59]
	v_mov_b32_e32 v62, v61
	v_fma_f32 v48, |v46|, s54, 1.0
	v_rcp_f32_e32 v48, v48
	v_lshlrev_b32_e32 v61, 16, v52
	v_mul_f32_e32 v44, v44, v61
	v_cmp_gt_f32_e64 s[4:5], 0, v46
	v_fmamk_f32 v49, v48, 0x3f07dc22, v225
	v_fmaak_f32 v49, v48, v49, 0x3f35f0e3
	v_fmaak_f32 v49, v48, v49, 0xbe11a98e
	v_fmaak_f32 v49, v48, v49, 0x3e027906
	v_mul_f32_e32 v50, v48, v49
	v_pk_mul_f32 v[48:49], v[46:47], v[46:47]
	v_cvt_pk_bf16_f32 v44, v44, v45
	v_lshlrev_b32_e32 v45, 16, v53
	v_mul_f32_e32 v48, 0xbf38aa3b, v48
	v_exp_f32_e32 v48, v48
	v_cmp_gt_f32_e32 vcc, 0, v47
	v_and_b32_e32 v93, 0xffff0000, v42
	v_mov_b32_e32 v92, v69
	v_mul_f32_e32 v48, v48, v50
	v_mul_f32_e32 v50, v46, v48
	v_fma_f32 v48, -v46, v48, v46
	v_cndmask_b32_e64 v46, v48, v50, s[4:5]
	v_mul_f32_e32 v45, v46, v45
	v_fma_f32 v46, |v47|, s54, 1.0
	v_rcp_f32_e32 v46, v46
	v_pk_mul_f32 v[62:63], v[16:17], v[62:63]
	v_pk_mul_f32 v[92:93], v[24:25], v[92:93]
	v_mov_b32_e32 v61, v68
	v_fmamk_f32 v48, v46, 0x3f07dc22, v225
	v_fmaak_f32 v48, v46, v48, 0x3f35f0e3
	v_fmaak_f32 v48, v46, v48, 0xbe11a98e
	v_fmaak_f32 v48, v46, v48, 0x3e027906
	v_mul_f32_e32 v46, v46, v48
	v_mul_f32_e32 v48, 0xbf38aa3b, v49
	v_exp_f32_e32 v48, v48
	v_mov_b32_e32 v49, v92
	v_mov_b32_e32 v92, v63
	v_lshlrev_b32_e32 v50, 16, v54
	v_mul_f32_e32 v46, v48, v46
	v_mul_f32_e32 v48, v47, v46
	v_fma_f32 v46, -v47, v46, v47
	v_cndmask_b32_e32 v46, v46, v48, vcc
	v_and_b32_e32 v47, 0xffff0000, v53
	v_mul_f32_e32 v46, v46, v47
	v_cvt_pk_bf16_f32 v45, v45, v46
	v_pk_fma_f32 v[46:47], v[4:5], v[60:61], v[28:29]
	v_mov_b32_e32 v48, v62
	v_pk_add_f32 v[46:47], v[46:47], v[48:49]
	v_mov_b32_e32 v71, v108
	v_pk_add_f32 v[46:47], v[46:47], v[92:93]
	s_nop 0
	v_fma_f32 v48, |v46|, s54, 1.0
	v_rcp_f32_e32 v48, v48
	v_cmp_gt_f32_e64 s[4:5], 0, v46
	v_cmp_gt_f32_e32 vcc, 0, v47
	v_fmamk_f32 v49, v48, 0x3f07dc22, v225
	v_fmaak_f32 v49, v48, v49, 0x3f35f0e3
	v_fmaak_f32 v49, v48, v49, 0xbe11a98e
	v_fmaak_f32 v49, v48, v49, 0x3e027906
	v_mul_f32_e32 v51, v48, v49
	v_pk_mul_f32 v[48:49], v[46:47], v[46:47]
	s_nop 0
	v_mul_f32_e32 v48, 0xbf38aa3b, v48
	v_exp_f32_e32 v48, v48
	v_mul_f32_e32 v49, 0xbf38aa3b, v49
	v_exp_f32_e32 v49, v49
	v_mul_f32_e32 v48, v48, v51
	v_mul_f32_e32 v51, v46, v48
	v_fma_f32 v48, -v46, v48, v46
	v_cndmask_b32_e64 v46, v48, v51, s[4:5]
	v_fma_f32 v48, |v47|, s54, 1.0
	v_rcp_f32_e32 v48, v48
	v_mul_f32_e32 v46, v46, v50
	v_mov_b32_e32 v51, v96
	v_mov_b32_e32 v96, v95
	v_fmamk_f32 v50, v48, 0x3f07dc22, v225
	v_fmaak_f32 v50, v48, v50, 0x3f35f0e3
	v_fmaak_f32 v50, v48, v50, 0xbe11a98e
	v_fmaak_f32 v50, v48, v50, 0x3e027906
	v_mul_f32_e32 v48, v48, v50
	v_mul_f32_e32 v48, v49, v48
	v_mul_f32_e32 v49, v47, v48
	v_fma_f32 v47, -v47, v48, v47
	v_cndmask_b32_e32 v47, v47, v49, vcc
	v_and_b32_e32 v48, 0xffff0000, v54
	v_mul_f32_e32 v47, v47, v48
	v_pk_fma_f32 v[48:49], v[6:7], v[70:71], v[30:31]
	v_mov_b32_e32 v50, v94
	v_pk_add_f32 v[48:49], v[48:49], v[50:51]
	v_cvt_pk_bf16_f32 v46, v46, v47
	v_lshlrev_b32_e32 v47, 16, v55
	v_pk_add_f32 v[48:49], v[48:49], v[96:97]
	s_nop 0
	v_fma_f32 v50, |v48|, s54, 1.0
	v_rcp_f32_e32 v50, v50
	v_cmp_gt_f32_e64 s[4:5], 0, v48
	v_cmp_gt_f32_e32 vcc, 0, v49
	v_fmamk_f32 v51, v50, 0x3f07dc22, v225
	v_fmaak_f32 v51, v50, v51, 0x3f35f0e3
	v_fmaak_f32 v51, v50, v51, 0xbe11a98e
	v_fmaak_f32 v51, v50, v51, 0x3e027906
	v_mul_f32_e32 v52, v50, v51
	v_pk_mul_f32 v[50:51], v[48:49], v[48:49]
	s_nop 0
	v_mul_f32_e32 v50, 0xbf38aa3b, v50
	v_exp_f32_e32 v50, v50
	s_nop 0
	v_mul_f32_e32 v50, v50, v52
	v_mul_f32_e32 v52, v48, v50
	v_fma_f32 v50, -v48, v50, v48
	v_cndmask_b32_e64 v48, v50, v52, s[4:5]
	v_mul_f32_e32 v47, v48, v47
	v_fma_f32 v48, |v49|, s54, 1.0
	v_rcp_f32_e32 v48, v48
	s_mov_b64 s[4:5], 0x16000
	v_lshl_add_u64 v[88:89], v[88:89], 0, s[4:5]
	v_fmamk_f32 v50, v48, 0x3f07dc22, v225
	v_fmaak_f32 v50, v48, v50, 0x3f35f0e3
	v_fmaak_f32 v50, v48, v50, 0xbe11a98e
	v_fmaak_f32 v50, v48, v50, 0x3e027906
	v_mul_f32_e32 v48, v48, v50
	v_mul_f32_e32 v50, 0xbf38aa3b, v51
	v_exp_f32_e32 v50, v50
	s_nop 0
	v_mul_f32_e32 v48, v50, v48
	v_mul_f32_e32 v50, v49, v48
	v_fma_f32 v48, -v49, v48, v49
	v_cndmask_b32_e32 v48, v48, v50, vcc
	v_and_b32_e32 v49, 0xffff0000, v55
	v_mul_f32_e32 v48, v48, v49
	v_cvt_pk_bf16_f32 v47, v47, v48
	global_store_dwordx4 v[90:91], v[44:47], off offset:3072
	v_cmp_ge_i32_e32 vcc, v120, v2
	v_mov_b64_e32 v[50:51], v[42:43]
	v_mov_b64_e32 v[46:47], v[38:39]
	s_or_b64 s[10:11], vcc, s[10:11]
	v_mov_b64_e32 v[48:49], v[40:41]
	v_mov_b64_e32 v[44:45], v[36:37]
	s_andn2_b64 exec, exec, s[10:11]
	s_cbranch_execnz .LBB0_858

; __device__ __forceinline__ int opaque_tid(int wv) { asm volatile("" : "+s"(wv)); unsigned z = 0u; asm volatile("" : "+v"(z)); const int l = __builtin_amdgcn_mbcnt_hi(~0u, __builtin_amdgcn_mbcnt_lo(~0u, z)); return (wv << 6) | l; }
; __device__ __forceinline__ void final_phase(int wv, PP P) {
;     const float* hp = (const float*)(P->ws + WS_HP); const float* rsq = (const float*)(P->ws + WS_RSQ) + (size_t)4 * MP;
;     const int tid = opaque_tid(wv), w = tid >> 6, lane = tid & 63;
;     for (int orow = blockIdx.x * 8 + w; orow < NB * SEQ; orow += gridDim.x * 8) {
;         const int b = orow / SEQ, s = orow % SEQ; const size_t row = (size_t)b * LP + LEADR + s; const float r = rsqrtf(rsq[row] * (1.0f / D) + EPS);
; #pragma unroll
;         for (int i = 0; i < 8; ++i) { const int c = (i * 64 + lane) * 4; const f32x4 v = *(const f32x4*)(hp + row * D + c), g = *(const f32x4*)(P->norm_f + c);
;             *(f32x4*)(P->out + (size_t)orow * D + c) = v * g * r; }
;     }
; }
.LBB0_1021:
	v_mov_b32_e32 v0, 0
	v_readlane_b32 s2, v254, 0
	v_mbcnt_lo_u32_b32 v0, -1, v0
	v_mbcnt_hi_u32_b32 v0, -1, v0
	v_lshl_or_b32 v2, s95, 6, v0
	v_ashrrev_i32_e32 v2, 6, v2
	v_add_u32_e32 v2, s2, v2
	s_movk_i32 s2, 0x4000
	v_mov_b32_e32 v1, 0
	v_cmp_gt_i32_e32 vcc, s2, v2
	s_and_saveexec_b64 s[2:3], vcc
	s_cbranch_execz .LBB0_1024
	s_load_dwordx2 s[2:3], s[0:1], 0xa0
	s_load_dwordx4 s[4:7], s[0:1], 0x90
	v_lshlrev_b32_e32 v0, 4, v0
	v_mov_b32_e32 v142, 0x358637bd
	s_mov_b32 s9, 0x800000
	s_lshl_b32 s20, s81, 3
	s_add_u32 s20, s20, s95
	s_waitcnt lgkmcnt(0)
	global_load_dwordx4 v[40:43], v0, s[4:5]
	global_load_dwordx4 v[44:47], v0, s[4:5] offset:1024
	global_load_dwordx4 v[48:51], v0, s[4:5] offset:2048
	global_load_dwordx4 v[52:55], v0, s[4:5] offset:3072
	s_add_u32 s4, s4, 0x1000
	s_addc_u32 s5, s5, 0
	global_load_dwordx4 v[56:59], v0, s[4:5]
	global_load_dwordx4 v[60:63], v0, s[4:5] offset:1024
	global_load_dwordx4 v[64:67], v0, s[4:5] offset:2048
	global_load_dwordx4 v[68:71], v0, s[4:5] offset:3072
	s_add_u32 s21, s20, 64
	s_lshl_b32 s22, s21, 2
	s_add_u32 s10, s2, 0x27cc6000
	s_addc_u32 s11, s3, 0
	s_add_u32 s10, s10, s22
	s_addc_u32 s11, s11, 0
	s_lshl_b32 s22, s21, 13
	s_add_u32 s12, s2, s22
	s_addc_u32 s13, s3, 0
	s_lshl_b32 s22, s20, 13
	s_add_u32 s16, s6, s22
	s_addc_u32 s17, s7, 0
	s_add_u32 s18, s16, 0x1000
	s_addc_u32 s19, s17, 0
	s_add_u32 s14, s12, 0x1000
	s_addc_u32 s15, s13, 0
	global_load_dword v136, v1, s[10:11]
	global_load_dwordx4 v[72:75], v0, s[12:13]
	global_load_dwordx4 v[76:79], v0, s[12:13] offset:1024
	global_load_dwordx4 v[80:83], v0, s[12:13] offset:2048
	global_load_dwordx4 v[84:87], v0, s[12:13] offset:3072
	global_load_dwordx4 v[88:91], v0, s[14:15]
	global_load_dwordx4 v[92:95], v0, s[14:15] offset:1024
	global_load_dwordx4 v[96:99], v0, s[14:15] offset:2048
	global_load_dwordx4 v[100:103], v0, s[14:15] offset:3072
	s_add_u32 s10, s10, 0x2100
	s_addc_u32 s11, s11, 0
	s_add_u32 s12, s12, 0x1080000
	s_addc_u32 s13, s13, 0
	s_add_u32 s14, s12, 0x1000
	s_addc_u32 s15, s13, 0
	global_load_dword v137, v1, s[10:11]
	global_load_dwordx4 v[104:107], v0, s[12:13]
	global_load_dwordx4 v[108:111], v0, s[12:13] offset:1024
	global_load_dwordx4 v[112:115], v0, s[12:13] offset:2048
	global_load_dwordx4 v[116:119], v0, s[12:13] offset:3072
	global_load_dwordx4 v[120:123], v0, s[14:15]
	global_load_dwordx4 v[124:127], v0, s[14:15] offset:1024
	global_load_dwordx4 v[128:131], v0, s[14:15] offset:2048
	global_load_dwordx4 v[132:135], v0, s[14:15] offset:3072
	s_waitcnt vmcnt(9)
	v_fmamk_f32 v138, v136, 0x3a000000, v142
	v_mul_f32_e32 v139, 0x4b800000, v138
	v_cmp_gt_f32_e32 vcc, s9, v138
	v_pk_mul_f32 v[74:75], v[74:75], v[42:43]
	v_pk_mul_f32 v[72:73], v[72:73], v[40:41]
	v_cndmask_b32_e32 v138, v138, v139, vcc
	v_rsq_f32_e32 v138, v138
	v_pk_mul_f32 v[78:79], v[78:79], v[46:47]
	v_pk_mul_f32 v[76:77], v[76:77], v[44:45]
	v_mul_f32_e32 v139, 0x45800000, v138
	v_cndmask_b32_e32 v140, v138, v139, vcc
	v_pk_mul_f32 v[82:83], v[82:83], v[50:51]
	v_pk_mul_f32 v[80:81], v[80:81], v[48:49]
	v_pk_mul_f32 v[86:87], v[86:87], v[54:55]
	v_pk_mul_f32 v[84:85], v[84:85], v[52:53]
	v_pk_mul_f32 v[90:91], v[90:91], v[58:59]
	v_pk_mul_f32 v[88:89], v[88:89], v[56:57]
	v_pk_mul_f32 v[94:95], v[94:95], v[62:63]
	v_pk_mul_f32 v[92:93], v[92:93], v[60:61]
	v_pk_mul_f32 v[98:99], v[98:99], v[66:67]
	v_pk_mul_f32 v[96:97], v[96:97], v[64:65]
	v_pk_mul_f32 v[102:103], v[102:103], v[70:71]
	v_pk_mul_f32 v[100:101], v[100:101], v[68:69]
	v_pk_mul_f32 v[74:75], v[74:75], v[140:141] op_sel_hi:[1,0]
	v_pk_mul_f32 v[72:73], v[72:73], v[140:141] op_sel_hi:[1,0]
	v_pk_mul_f32 v[78:79], v[78:79], v[140:141] op_sel_hi:[1,0]
	v_pk_mul_f32 v[76:77], v[76:77], v[140:141] op_sel_hi:[1,0]
	v_pk_mul_f32 v[82:83], v[82:83], v[140:141] op_sel_hi:[1,0]
	v_pk_mul_f32 v[80:81], v[80:81], v[140:141] op_sel_hi:[1,0]
	v_pk_mul_f32 v[86:87], v[86:87], v[140:141] op_sel_hi:[1,0]
	v_pk_mul_f32 v[84:85], v[84:85], v[140:141] op_sel_hi:[1,0]
	v_pk_mul_f32 v[90:91], v[90:91], v[140:141] op_sel_hi:[1,0]
	v_pk_mul_f32 v[88:89], v[88:89], v[140:141] op_sel_hi:[1,0]
	v_pk_mul_f32 v[94:95], v[94:95], v[140:141] op_sel_hi:[1,0]
	v_pk_mul_f32 v[92:93], v[92:93], v[140:141] op_sel_hi:[1,0]
	v_pk_mul_f32 v[98:99], v[98:99], v[140:141] op_sel_hi:[1,0]
	v_pk_mul_f32 v[96:97], v[96:97], v[140:141] op_sel_hi:[1,0]
	v_pk_mul_f32 v[102:103], v[102:103], v[140:141] op_sel_hi:[1,0]
	v_pk_mul_f32 v[100:101], v[100:101], v[140:141] op_sel_hi:[1,0]
	global_store_dwordx4 v0, v[72:75], s[16:17]
	global_store_dwordx4 v0, v[76:79], s[16:17] offset:1024
	global_store_dwordx4 v0, v[80:83], s[16:17] offset:2048
	global_store_dwordx4 v0, v[84:87], s[16:17] offset:3072
	global_store_dwordx4 v0, v[88:91], s[18:19]
	global_store_dwordx4 v0, v[92:95], s[18:19] offset:1024
	global_store_dwordx4 v0, v[96:99], s[18:19] offset:2048
	global_store_dwordx4 v0, v[100:103], s[18:19] offset:3072
	s_add_u32 s16, s16, 0x1000000
	s_addc_u32 s17, s17, 0
	s_add_u32 s18, s18, 0x1000000
	s_addc_u32 s19, s19, 0
	s_add_u32 s10, s10, 0x2100
	s_addc_u32 s11, s11, 0
	s_add_u32 s12, s12, 0x1080000
	s_addc_u32 s13, s13, 0
	s_add_u32 s14, s12, 0x1000
	s_addc_u32 s15, s13, 0
	global_load_dword v136, v1, s[10:11]
	global_load_dwordx4 v[72:75], v0, s[12:13]
	global_load_dwordx4 v[76:79], v0, s[12:13] offset:1024
	global_load_dwordx4 v[80:83], v0, s[12:13] offset:2048
	global_load_dwordx4 v[84:87], v0, s[12:13] offset:3072
	global_load_dwordx4 v[88:91], v0, s[14:15]
	global_load_dwordx4 v[92:95], v0, s[14:15] offset:1024
	global_load_dwordx4 v[96:99], v0, s[14:15] offset:2048
	global_load_dwordx4 v[100:103], v0, s[14:15] offset:3072
	s_waitcnt vmcnt(17)
; __device__ __forceinline__ void final_phase(int wv, PP P) {
;     ...
;     for (int orow = blockIdx.x * 8 + w; orow < NB * SEQ; orow += gridDim.x * 8) {
;         const int b = orow / SEQ, s = orow % SEQ; const size_t row = (size_t)b * LP + LEADR + s; const float r = rsqrtf(rsq[row] * (1.0f / D) + EPS);
; #pragma unroll
;         for (int i = 0; i < 8; ++i) { const int c = (i * 64 + lane) * 4; const f32x4 v = *(const f32x4*)(hp + row * D + c), g = *(const f32x4*)(P->norm_f + c);
;             *(f32x4*)(P->out + (size_t)orow * D + c) = v * g * r; }
;     }
	v_fmamk_f32 v138, v137, 0x3a000000, v142
	v_mul_f32_e32 v139, 0x4b800000, v138
	v_cmp_gt_f32_e32 vcc, s9, v138
	v_pk_mul_f32 v[106:107], v[106:107], v[42:43]
	v_pk_mul_f32 v[104:105], v[104:105], v[40:41]
	v_cndmask_b32_e32 v138, v138, v139, vcc
	v_rsq_f32_e32 v138, v138
	v_pk_mul_f32 v[110:111], v[110:111], v[46:47]
	v_pk_mul_f32 v[108:109], v[108:109], v[44:45]
	v_mul_f32_e32 v139, 0x45800000, v138
	v_cndmask_b32_e32 v140, v138, v139, vcc
	v_pk_mul_f32 v[114:115], v[114:115], v[50:51]
	v_pk_mul_f32 v[112:113], v[112:113], v[48:49]
	v_pk_mul_f32 v[118:119], v[118:119], v[54:55]
	v_pk_mul_f32 v[116:117], v[116:117], v[52:53]
	v_pk_mul_f32 v[122:123], v[122:123], v[58:59]
	v_pk_mul_f32 v[120:121], v[120:121], v[56:57]
	v_pk_mul_f32 v[126:127], v[126:127], v[62:63]
	v_pk_mul_f32 v[124:125], v[124:125], v[60:61]
	v_pk_mul_f32 v[130:131], v[130:131], v[66:67]
	v_pk_mul_f32 v[128:129], v[128:129], v[64:65]
	v_pk_mul_f32 v[134:135], v[134:135], v[70:71]
	v_pk_mul_f32 v[132:133], v[132:133], v[68:69]
	v_pk_mul_f32 v[106:107], v[106:107], v[140:141] op_sel_hi:[1,0]
	v_pk_mul_f32 v[104:105], v[104:105], v[140:141] op_sel_hi:[1,0]
	v_pk_mul_f32 v[110:111], v[110:111], v[140:141] op_sel_hi:[1,0]
	v_pk_mul_f32 v[108:109], v[108:109], v[140:141] op_sel_hi:[1,0]
	v_pk_mul_f32 v[114:115], v[114:115], v[140:141] op_sel_hi:[1,0]
	v_pk_mul_f32 v[112:113], v[112:113], v[140:141] op_sel_hi:[1,0]
	v_pk_mul_f32 v[118:119], v[118:119], v[140:141] op_sel_hi:[1,0]
	v_pk_mul_f32 v[116:117], v[116:117], v[140:141] op_sel_hi:[1,0]
	v_pk_mul_f32 v[122:123], v[122:123], v[140:141] op_sel_hi:[1,0]
	v_pk_mul_f32 v[120:121], v[120:121], v[140:141] op_sel_hi:[1,0]
	v_pk_mul_f32 v[126:127], v[126:127], v[140:141] op_sel_hi:[1,0]
	v_pk_mul_f32 v[124:125], v[124:125], v[140:141] op_sel_hi:[1,0]
	v_pk_mul_f32 v[130:131], v[130:131], v[140:141] op_sel_hi:[1,0]
	v_pk_mul_f32 v[128:129], v[128:129], v[140:141] op_sel_hi:[1,0]
	v_pk_mul_f32 v[134:135], v[134:135], v[140:141] op_sel_hi:[1,0]
	v_pk_mul_f32 v[132:133], v[132:133], v[140:141] op_sel_hi:[1,0]
	global_store_dwordx4 v0, v[104:107], s[16:17]
	global_store_dwordx4 v0, v[108:111], s[16:17] offset:1024
	global_store_dwordx4 v0, v[112:115], s[16:17] offset:2048
	global_store_dwordx4 v0, v[116:119], s[16:17] offset:3072
	global_store_dwordx4 v0, v[120:123], s[18:19]
	global_store_dwordx4 v0, v[124:127], s[18:19] offset:1024
	global_store_dwordx4 v0, v[128:131], s[18:19] offset:2048
	global_store_dwordx4 v0, v[132:135], s[18:19] offset:3072
	s_add_u32 s16, s16, 0x1000000
	s_addc_u32 s17, s17, 0
	s_add_u32 s18, s18, 0x1000000
	s_addc_u32 s19, s19, 0
	s_add_u32 s10, s10, 0x2100
	s_addc_u32 s11, s11, 0
	s_add_u32 s12, s12, 0x1080000
	s_addc_u32 s13, s13, 0
	s_add_u32 s14, s12, 0x1000
	s_addc_u32 s15, s13, 0
	global_load_dword v137, v1, s[10:11]
	global_load_dwordx4 v[104:107], v0, s[12:13]
	global_load_dwordx4 v[108:111], v0, s[12:13] offset:1024
	global_load_dwordx4 v[112:115], v0, s[12:13] offset:2048
	global_load_dwordx4 v[116:119], v0, s[12:13] offset:3072
	global_load_dwordx4 v[120:123], v0, s[14:15]
	global_load_dwordx4 v[124:127], v0, s[14:15] offset:1024
	global_load_dwordx4 v[128:131], v0, s[14:15] offset:2048
	global_load_dwordx4 v[132:135], v0, s[14:15] offset:3072
	s_waitcnt vmcnt(17)
	v_fmamk_f32 v138, v136, 0x3a000000, v142
	v_mul_f32_e32 v139, 0x4b800000, v138
	v_cmp_gt_f32_e32 vcc, s9, v138
	v_pk_mul_f32 v[74:75], v[74:75], v[42:43]
	v_pk_mul_f32 v[72:73], v[72:73], v[40:41]
	v_cndmask_b32_e32 v138, v138, v139, vcc
	v_rsq_f32_e32 v138, v138
	v_pk_mul_f32 v[78:79], v[78:79], v[46:47]
	v_pk_mul_f32 v[76:77], v[76:77], v[44:45]
	v_mul_f32_e32 v139, 0x45800000, v138
	v_cndmask_b32_e32 v140, v138, v139, vcc
	v_pk_mul_f32 v[82:83], v[82:83], v[50:51]
	v_pk_mul_f32 v[80:81], v[80:81], v[48:49]
	v_pk_mul_f32 v[86:87], v[86:87], v[54:55]
	v_pk_mul_f32 v[84:85], v[84:85], v[52:53]
	v_pk_mul_f32 v[90:91], v[90:91], v[58:59]
	v_pk_mul_f32 v[88:89], v[88:89], v[56:57]
	v_pk_mul_f32 v[94:95], v[94:95], v[62:63]
	v_pk_mul_f32 v[92:93], v[92:93], v[60:61]
	v_pk_mul_f32 v[98:99], v[98:99], v[66:67]
	v_pk_mul_f32 v[96:97], v[96:97], v[64:65]
	v_pk_mul_f32 v[102:103], v[102:103], v[70:71]
	v_pk_mul_f32 v[100:101], v[100:101], v[68:69]
	v_pk_mul_f32 v[74:75], v[74:75], v[140:141] op_sel_hi:[1,0]
	v_pk_mul_f32 v[72:73], v[72:73], v[140:141] op_sel_hi:[1,0]
	v_pk_mul_f32 v[78:79], v[78:79], v[140:141] op_sel_hi:[1,0]
	v_pk_mul_f32 v[76:77], v[76:77], v[140:141] op_sel_hi:[1,0]
	v_pk_mul_f32 v[82:83], v[82:83], v[140:141] op_sel_hi:[1,0]
	v_pk_mul_f32 v[80:81], v[80:81], v[140:141] op_sel_hi:[1,0]
	v_pk_mul_f32 v[86:87], v[86:87], v[140:141] op_sel_hi:[1,0]
	v_pk_mul_f32 v[84:85], v[84:85], v[140:141] op_sel_hi:[1,0]
	v_pk_mul_f32 v[90:91], v[90:91], v[140:141] op_sel_hi:[1,0]
	v_pk_mul_f32 v[88:89], v[88:89], v[140:141] op_sel_hi:[1,0]
	v_pk_mul_f32 v[94:95], v[94:95], v[140:141] op_sel_hi:[1,0]
	v_pk_mul_f32 v[92:93], v[92:93], v[140:141] op_sel_hi:[1,0]
	v_pk_mul_f32 v[98:99], v[98:99], v[140:141] op_sel_hi:[1,0]
	v_pk_mul_f32 v[96:97], v[96:97], v[140:141] op_sel_hi:[1,0]
	v_pk_mul_f32 v[102:103], v[102:103], v[140:141] op_sel_hi:[1,0]
	v_pk_mul_f32 v[100:101], v[100:101], v[140:141] op_sel_hi:[1,0]
	global_store_dwordx4 v0, v[72:75], s[16:17]
	global_store_dwordx4 v0, v[76:79], s[16:17] offset:1024
	global_store_dwordx4 v0, v[80:83], s[16:17] offset:2048
	global_store_dwordx4 v0, v[84:87], s[16:17] offset:3072
	global_store_dwordx4 v0, v[88:91], s[18:19]
	global_store_dwordx4 v0, v[92:95], s[18:19] offset:1024
	global_store_dwordx4 v0, v[96:99], s[18:19] offset:2048
	global_store_dwordx4 v0, v[100:103], s[18:19] offset:3072
	s_add_u32 s16, s16, 0x1000000
	s_addc_u32 s17, s17, 0
	s_add_u32 s18, s18, 0x1000000
	s_addc_u32 s19, s19, 0
	s_add_u32 s10, s10, 0x2100
	s_addc_u32 s11, s11, 0
	s_add_u32 s12, s12, 0x1080000
	s_addc_u32 s13, s13, 0
	s_add_u32 s14, s12, 0x1000
	s_addc_u32 s15, s13, 0
	global_load_dword v136, v1, s[10:11]
	global_load_dwordx4 v[72:75], v0, s[12:13]
	global_load_dwordx4 v[76:79], v0, s[12:13] offset:1024
	global_load_dwordx4 v[80:83], v0, s[12:13] offset:2048
	global_load_dwordx4 v[84:87], v0, s[12:13] offset:3072
	global_load_dwordx4 v[88:91], v0, s[14:15]
	global_load_dwordx4 v[92:95], v0, s[14:15] offset:1024
	global_load_dwordx4 v[96:99], v0, s[14:15] offset:2048
	global_load_dwordx4 v[100:103], v0, s[14:15] offset:3072
	s_waitcnt vmcnt(17)
; __device__ __forceinline__ void final_phase(int wv, PP P) {
;     ...
;     for (int orow = blockIdx.x * 8 + w; orow < NB * SEQ; orow += gridDim.x * 8) {
;         const int b = orow / SEQ, s = orow % SEQ; const size_t row = (size_t)b * LP + LEADR + s; const float r = rsqrtf(rsq[row] * (1.0f / D) + EPS);
; #pragma unroll
;         for (int i = 0; i < 8; ++i) { const int c = (i * 64 + lane) * 4; const f32x4 v = *(const f32x4*)(hp + row * D + c), g = *(const f32x4*)(P->norm_f + c);
;             *(f32x4*)(P->out + (size_t)orow * D + c) = v * g * r; }
;     }
	v_fmamk_f32 v138, v137, 0x3a000000, v142
	v_mul_f32_e32 v139, 0x4b800000, v138
	v_cmp_gt_f32_e32 vcc, s9, v138
	v_pk_mul_f32 v[106:107], v[106:107], v[42:43]
	v_pk_mul_f32 v[104:105], v[104:105], v[40:41]
	v_cndmask_b32_e32 v138, v138, v139, vcc
	v_rsq_f32_e32 v138, v138
	v_pk_mul_f32 v[110:111], v[110:111], v[46:47]
	v_pk_mul_f32 v[108:109], v[108:109], v[44:45]
	v_mul_f32_e32 v139, 0x45800000, v138
	v_cndmask_b32_e32 v140, v138, v139, vcc
	v_pk_mul_f32 v[114:115], v[114:115], v[50:51]
	v_pk_mul_f32 v[112:113], v[112:113], v[48:49]
	v_pk_mul_f32 v[118:119], v[118:119], v[54:55]
	v_pk_mul_f32 v[116:117], v[116:117], v[52:53]
	v_pk_mul_f32 v[122:123], v[122:123], v[58:59]
	v_pk_mul_f32 v[120:121], v[120:121], v[56:57]
	v_pk_mul_f32 v[126:127], v[126:127], v[62:63]
	v_pk_mul_f32 v[124:125], v[124:125], v[60:61]
	v_pk_mul_f32 v[130:131], v[130:131], v[66:67]
	v_pk_mul_f32 v[128:129], v[128:129], v[64:65]
	v_pk_mul_f32 v[134:135], v[134:135], v[70:71]
	v_pk_mul_f32 v[132:133], v[132:133], v[68:69]
	v_pk_mul_f32 v[106:107], v[106:107], v[140:141] op_sel_hi:[1,0]
	v_pk_mul_f32 v[104:105], v[104:105], v[140:141] op_sel_hi:[1,0]
	v_pk_mul_f32 v[110:111], v[110:111], v[140:141] op_sel_hi:[1,0]
	v_pk_mul_f32 v[108:109], v[108:109], v[140:141] op_sel_hi:[1,0]
	v_pk_mul_f32 v[114:115], v[114:115], v[140:141] op_sel_hi:[1,0]
	v_pk_mul_f32 v[112:113], v[112:113], v[140:141] op_sel_hi:[1,0]
	v_pk_mul_f32 v[118:119], v[118:119], v[140:141] op_sel_hi:[1,0]
	v_pk_mul_f32 v[116:117], v[116:117], v[140:141] op_sel_hi:[1,0]
	v_pk_mul_f32 v[122:123], v[122:123], v[140:141] op_sel_hi:[1,0]
	v_pk_mul_f32 v[120:121], v[120:121], v[140:141] op_sel_hi:[1,0]
	v_pk_mul_f32 v[126:127], v[126:127], v[140:141] op_sel_hi:[1,0]
	v_pk_mul_f32 v[124:125], v[124:125], v[140:141] op_sel_hi:[1,0]
	v_pk_mul_f32 v[130:131], v[130:131], v[140:141] op_sel_hi:[1,0]
	v_pk_mul_f32 v[128:129], v[128:129], v[140:141] op_sel_hi:[1,0]
	v_pk_mul_f32 v[134:135], v[134:135], v[140:141] op_sel_hi:[1,0]
	v_pk_mul_f32 v[132:133], v[132:133], v[140:141] op_sel_hi:[1,0]
	global_store_dwordx4 v0, v[104:107], s[16:17]
	global_store_dwordx4 v0, v[108:111], s[16:17] offset:1024
	global_store_dwordx4 v0, v[112:115], s[16:17] offset:2048
	global_store_dwordx4 v0, v[116:119], s[16:17] offset:3072
	global_store_dwordx4 v0, v[120:123], s[18:19]
	global_store_dwordx4 v0, v[124:127], s[18:19] offset:1024
	global_store_dwordx4 v0, v[128:131], s[18:19] offset:2048
	global_store_dwordx4 v0, v[132:135], s[18:19] offset:3072
	s_add_u32 s16, s16, 0x1000000
	s_addc_u32 s17, s17, 0
	s_add_u32 s18, s18, 0x1000000
	s_addc_u32 s19, s19, 0
	s_add_u32 s10, s10, 0x2100
	s_addc_u32 s11, s11, 0
	s_add_u32 s12, s12, 0x1080000
	s_addc_u32 s13, s13, 0
	s_add_u32 s14, s12, 0x1000
	s_addc_u32 s15, s13, 0
	global_load_dword v137, v1, s[10:11]
	global_load_dwordx4 v[104:107], v0, s[12:13]
	global_load_dwordx4 v[108:111], v0, s[12:13] offset:1024
	global_load_dwordx4 v[112:115], v0, s[12:13] offset:2048
	global_load_dwordx4 v[116:119], v0, s[12:13] offset:3072
	global_load_dwordx4 v[120:123], v0, s[14:15]
	global_load_dwordx4 v[124:127], v0, s[14:15] offset:1024
	global_load_dwordx4 v[128:131], v0, s[14:15] offset:2048
	global_load_dwordx4 v[132:135], v0, s[14:15] offset:3072
	s_waitcnt vmcnt(17)
	v_fmamk_f32 v138, v136, 0x3a000000, v142
	v_mul_f32_e32 v139, 0x4b800000, v138
	v_cmp_gt_f32_e32 vcc, s9, v138
	v_pk_mul_f32 v[74:75], v[74:75], v[42:43]
	v_pk_mul_f32 v[72:73], v[72:73], v[40:41]
	v_cndmask_b32_e32 v138, v138, v139, vcc
	v_rsq_f32_e32 v138, v138
	v_pk_mul_f32 v[78:79], v[78:79], v[46:47]
	v_pk_mul_f32 v[76:77], v[76:77], v[44:45]
	v_mul_f32_e32 v139, 0x45800000, v138
	v_cndmask_b32_e32 v140, v138, v139, vcc
	v_pk_mul_f32 v[82:83], v[82:83], v[50:51]
	v_pk_mul_f32 v[80:81], v[80:81], v[48:49]
	v_pk_mul_f32 v[86:87], v[86:87], v[54:55]
	v_pk_mul_f32 v[84:85], v[84:85], v[52:53]
	v_pk_mul_f32 v[90:91], v[90:91], v[58:59]
	v_pk_mul_f32 v[88:89], v[88:89], v[56:57]
	v_pk_mul_f32 v[94:95], v[94:95], v[62:63]
	v_pk_mul_f32 v[92:93], v[92:93], v[60:61]
	v_pk_mul_f32 v[98:99], v[98:99], v[66:67]
	v_pk_mul_f32 v[96:97], v[96:97], v[64:65]
	v_pk_mul_f32 v[102:103], v[102:103], v[70:71]
	v_pk_mul_f32 v[100:101], v[100:101], v[68:69]
	v_pk_mul_f32 v[74:75], v[74:75], v[140:141] op_sel_hi:[1,0]
	v_pk_mul_f32 v[72:73], v[72:73], v[140:141] op_sel_hi:[1,0]
	v_pk_mul_f32 v[78:79], v[78:79], v[140:141] op_sel_hi:[1,0]
	v_pk_mul_f32 v[76:77], v[76:77], v[140:141] op_sel_hi:[1,0]
	v_pk_mul_f32 v[82:83], v[82:83], v[140:141] op_sel_hi:[1,0]
	v_pk_mul_f32 v[80:81], v[80:81], v[140:141] op_sel_hi:[1,0]
	v_pk_mul_f32 v[86:87], v[86:87], v[140:141] op_sel_hi:[1,0]
	v_pk_mul_f32 v[84:85], v[84:85], v[140:141] op_sel_hi:[1,0]
	v_pk_mul_f32 v[90:91], v[90:91], v[140:141] op_sel_hi:[1,0]
	v_pk_mul_f32 v[88:89], v[88:89], v[140:141] op_sel_hi:[1,0]
	v_pk_mul_f32 v[94:95], v[94:95], v[140:141] op_sel_hi:[1,0]
	v_pk_mul_f32 v[92:93], v[92:93], v[140:141] op_sel_hi:[1,0]
	v_pk_mul_f32 v[98:99], v[98:99], v[140:141] op_sel_hi:[1,0]
	v_pk_mul_f32 v[96:97], v[96:97], v[140:141] op_sel_hi:[1,0]
	v_pk_mul_f32 v[102:103], v[102:103], v[140:141] op_sel_hi:[1,0]
	v_pk_mul_f32 v[100:101], v[100:101], v[140:141] op_sel_hi:[1,0]
	global_store_dwordx4 v0, v[72:75], s[16:17]
	global_store_dwordx4 v0, v[76:79], s[16:17] offset:1024
	global_store_dwordx4 v0, v[80:83], s[16:17] offset:2048
	global_store_dwordx4 v0, v[84:87], s[16:17] offset:3072
	global_store_dwordx4 v0, v[88:91], s[18:19]
	global_store_dwordx4 v0, v[92:95], s[18:19] offset:1024
	global_store_dwordx4 v0, v[96:99], s[18:19] offset:2048
	global_store_dwordx4 v0, v[100:103], s[18:19] offset:3072
	s_add_u32 s16, s16, 0x1000000
	s_addc_u32 s17, s17, 0
	s_add_u32 s18, s18, 0x1000000
	s_addc_u32 s19, s19, 0
	s_add_u32 s10, s10, 0x2100
	s_addc_u32 s11, s11, 0
	s_add_u32 s12, s12, 0x1080000
	s_addc_u32 s13, s13, 0
	s_add_u32 s14, s12, 0x1000
	s_addc_u32 s15, s13, 0
	global_load_dword v136, v1, s[10:11]
	global_load_dwordx4 v[72:75], v0, s[12:13]
	global_load_dwordx4 v[76:79], v0, s[12:13] offset:1024
	global_load_dwordx4 v[80:83], v0, s[12:13] offset:2048
	global_load_dwordx4 v[84:87], v0, s[12:13] offset:3072
	global_load_dwordx4 v[88:91], v0, s[14:15]
	global_load_dwordx4 v[92:95], v0, s[14:15] offset:1024
	global_load_dwordx4 v[96:99], v0, s[14:15] offset:2048
	global_load_dwordx4 v[100:103], v0, s[14:15] offset:3072
	s_waitcnt vmcnt(17)
; __device__ __forceinline__ void final_phase(int wv, PP P) {
;     ...
;     for (int orow = blockIdx.x * 8 + w; orow < NB * SEQ; orow += gridDim.x * 8) {
;         const int b = orow / SEQ, s = orow % SEQ; const size_t row = (size_t)b * LP + LEADR + s; const float r = rsqrtf(rsq[row] * (1.0f / D) + EPS);
; #pragma unroll
;         for (int i = 0; i < 8; ++i) { const int c = (i * 64 + lane) * 4; const f32x4 v = *(const f32x4*)(hp + row * D + c), g = *(const f32x4*)(P->norm_f + c);
;             *(f32x4*)(P->out + (size_t)orow * D + c) = v * g * r; }
;     }
	v_fmamk_f32 v138, v137, 0x3a000000, v142
	v_mul_f32_e32 v139, 0x4b800000, v138
	v_cmp_gt_f32_e32 vcc, s9, v138
	v_pk_mul_f32 v[106:107], v[106:107], v[42:43]
	v_pk_mul_f32 v[104:105], v[104:105], v[40:41]
	v_cndmask_b32_e32 v138, v138, v139, vcc
	v_rsq_f32_e32 v138, v138
	v_pk_mul_f32 v[110:111], v[110:111], v[46:47]
	v_pk_mul_f32 v[108:109], v[108:109], v[44:45]
	v_mul_f32_e32 v139, 0x45800000, v138
	v_cndmask_b32_e32 v140, v138, v139, vcc
	v_pk_mul_f32 v[114:115], v[114:115], v[50:51]
	v_pk_mul_f32 v[112:113], v[112:113], v[48:49]
	v_pk_mul_f32 v[118:119], v[118:119], v[54:55]
	v_pk_mul_f32 v[116:117], v[116:117], v[52:53]
	v_pk_mul_f32 v[122:123], v[122:123], v[58:59]
	v_pk_mul_f32 v[120:121], v[120:121], v[56:57]
	v_pk_mul_f32 v[126:127], v[126:127], v[62:63]
	v_pk_mul_f32 v[124:125], v[124:125], v[60:61]
	v_pk_mul_f32 v[130:131], v[130:131], v[66:67]
	v_pk_mul_f32 v[128:129], v[128:129], v[64:65]
	v_pk_mul_f32 v[134:135], v[134:135], v[70:71]
	v_pk_mul_f32 v[132:133], v[132:133], v[68:69]
	v_pk_mul_f32 v[106:107], v[106:107], v[140:141] op_sel_hi:[1,0]
	v_pk_mul_f32 v[104:105], v[104:105], v[140:141] op_sel_hi:[1,0]
	v_pk_mul_f32 v[110:111], v[110:111], v[140:141] op_sel_hi:[1,0]
	v_pk_mul_f32 v[108:109], v[108:109], v[140:141] op_sel_hi:[1,0]
	v_pk_mul_f32 v[114:115], v[114:115], v[140:141] op_sel_hi:[1,0]
	v_pk_mul_f32 v[112:113], v[112:113], v[140:141] op_sel_hi:[1,0]
	v_pk_mul_f32 v[118:119], v[118:119], v[140:141] op_sel_hi:[1,0]
	v_pk_mul_f32 v[116:117], v[116:117], v[140:141] op_sel_hi:[1,0]
	v_pk_mul_f32 v[122:123], v[122:123], v[140:141] op_sel_hi:[1,0]
	v_pk_mul_f32 v[120:121], v[120:121], v[140:141] op_sel_hi:[1,0]
	v_pk_mul_f32 v[126:127], v[126:127], v[140:141] op_sel_hi:[1,0]
	v_pk_mul_f32 v[124:125], v[124:125], v[140:141] op_sel_hi:[1,0]
	v_pk_mul_f32 v[130:131], v[130:131], v[140:141] op_sel_hi:[1,0]
	v_pk_mul_f32 v[128:129], v[128:129], v[140:141] op_sel_hi:[1,0]
	v_pk_mul_f32 v[134:135], v[134:135], v[140:141] op_sel_hi:[1,0]
	v_pk_mul_f32 v[132:133], v[132:133], v[140:141] op_sel_hi:[1,0]
	global_store_dwordx4 v0, v[104:107], s[16:17]
	global_store_dwordx4 v0, v[108:111], s[16:17] offset:1024
	global_store_dwordx4 v0, v[112:115], s[16:17] offset:2048
	global_store_dwordx4 v0, v[116:119], s[16:17] offset:3072
	global_store_dwordx4 v0, v[120:123], s[18:19]
	global_store_dwordx4 v0, v[124:127], s[18:19] offset:1024
	global_store_dwordx4 v0, v[128:131], s[18:19] offset:2048
	global_store_dwordx4 v0, v[132:135], s[18:19] offset:3072
	s_add_u32 s16, s16, 0x1000000
	s_addc_u32 s17, s17, 0
	s_add_u32 s18, s18, 0x1000000
	s_addc_u32 s19, s19, 0
	s_add_u32 s10, s10, 0x2100
	s_addc_u32 s11, s11, 0
	s_add_u32 s12, s12, 0x1080000
	s_addc_u32 s13, s13, 0
	s_add_u32 s14, s12, 0x1000
	s_addc_u32 s15, s13, 0
	global_load_dword v137, v1, s[10:11]
	global_load_dwordx4 v[104:107], v0, s[12:13]
	global_load_dwordx4 v[108:111], v0, s[12:13] offset:1024
	global_load_dwordx4 v[112:115], v0, s[12:13] offset:2048
	global_load_dwordx4 v[116:119], v0, s[12:13] offset:3072
	global_load_dwordx4 v[120:123], v0, s[14:15]
	global_load_dwordx4 v[124:127], v0, s[14:15] offset:1024
	global_load_dwordx4 v[128:131], v0, s[14:15] offset:2048
	global_load_dwordx4 v[132:135], v0, s[14:15] offset:3072
	s_waitcnt vmcnt(17)
; __device__ __forceinline__ void final_phase(int wv, PP P) {
;     ...
;     for (int orow = blockIdx.x * 8 + w; orow < NB * SEQ; orow += gridDim.x * 8) {
;         const int b = orow / SEQ, s = orow % SEQ; const size_t row = (size_t)b * LP + LEADR + s; const float r = rsqrtf(rsq[row] * (1.0f / D) + EPS);
; #pragma unroll
;         for (int i = 0; i < 8; ++i) { const int c = (i * 64 + lane) * 4; const f32x4 v = *(const f32x4*)(hp + row * D + c), g = *(const f32x4*)(P->norm_f + c);
;             *(f32x4*)(P->out + (size_t)orow * D + c) = v * g * r; }
;     }
	v_fmamk_f32 v138, v136, 0x3a000000, v142
	v_mul_f32_e32 v139, 0x4b800000, v138
	v_cmp_gt_f32_e32 vcc, s9, v138
	v_pk_mul_f32 v[74:75], v[74:75], v[42:43]
	v_pk_mul_f32 v[72:73], v[72:73], v[40:41]
	v_cndmask_b32_e32 v138, v138, v139, vcc
	v_rsq_f32_e32 v138, v138
	v_pk_mul_f32 v[78:79], v[78:79], v[46:47]
	v_pk_mul_f32 v[76:77], v[76:77], v[44:45]
	v_mul_f32_e32 v139, 0x45800000, v138
	v_cndmask_b32_e32 v140, v138, v139, vcc
	v_pk_mul_f32 v[82:83], v[82:83], v[50:51]
	v_pk_mul_f32 v[80:81], v[80:81], v[48:49]
	v_pk_mul_f32 v[86:87], v[86:87], v[54:55]
	v_pk_mul_f32 v[84:85], v[84:85], v[52:53]
	v_pk_mul_f32 v[90:91], v[90:91], v[58:59]
	v_pk_mul_f32 v[88:89], v[88:89], v[56:57]
	v_pk_mul_f32 v[94:95], v[94:95], v[62:63]
	v_pk_mul_f32 v[92:93], v[92:93], v[60:61]
	v_pk_mul_f32 v[98:99], v[98:99], v[66:67]
	v_pk_mul_f32 v[96:97], v[96:97], v[64:65]
	v_pk_mul_f32 v[102:103], v[102:103], v[70:71]
	v_pk_mul_f32 v[100:101], v[100:101], v[68:69]
	v_pk_mul_f32 v[74:75], v[74:75], v[140:141] op_sel_hi:[1,0]
	v_pk_mul_f32 v[72:73], v[72:73], v[140:141] op_sel_hi:[1,0]
	v_pk_mul_f32 v[78:79], v[78:79], v[140:141] op_sel_hi:[1,0]
	v_pk_mul_f32 v[76:77], v[76:77], v[140:141] op_sel_hi:[1,0]
	v_pk_mul_f32 v[82:83], v[82:83], v[140:141] op_sel_hi:[1,0]
	v_pk_mul_f32 v[80:81], v[80:81], v[140:141] op_sel_hi:[1,0]
	v_pk_mul_f32 v[86:87], v[86:87], v[140:141] op_sel_hi:[1,0]
	v_pk_mul_f32 v[84:85], v[84:85], v[140:141] op_sel_hi:[1,0]
	v_pk_mul_f32 v[90:91], v[90:91], v[140:141] op_sel_hi:[1,0]
	v_pk_mul_f32 v[88:89], v[88:89], v[140:141] op_sel_hi:[1,0]
	v_pk_mul_f32 v[94:95], v[94:95], v[140:141] op_sel_hi:[1,0]
	v_pk_mul_f32 v[92:93], v[92:93], v[140:141] op_sel_hi:[1,0]
	v_pk_mul_f32 v[98:99], v[98:99], v[140:141] op_sel_hi:[1,0]
	v_pk_mul_f32 v[96:97], v[96:97], v[140:141] op_sel_hi:[1,0]
	v_pk_mul_f32 v[102:103], v[102:103], v[140:141] op_sel_hi:[1,0]
	v_pk_mul_f32 v[100:101], v[100:101], v[140:141] op_sel_hi:[1,0]
	global_store_dwordx4 v0, v[72:75], s[16:17]
	global_store_dwordx4 v0, v[76:79], s[16:17] offset:1024
	global_store_dwordx4 v0, v[80:83], s[16:17] offset:2048
	global_store_dwordx4 v0, v[84:87], s[16:17] offset:3072
	global_store_dwordx4 v0, v[88:91], s[18:19]
	global_store_dwordx4 v0, v[92:95], s[18:19] offset:1024
	global_store_dwordx4 v0, v[96:99], s[18:19] offset:2048
	global_store_dwordx4 v0, v[100:103], s[18:19] offset:3072
	s_add_u32 s16, s16, 0x1000000
	s_addc_u32 s17, s17, 0
	s_add_u32 s18, s18, 0x1000000
	s_addc_u32 s19, s19, 0
	s_waitcnt vmcnt(8)
	v_fmamk_f32 v138, v137, 0x3a000000, v142
	v_mul_f32_e32 v139, 0x4b800000, v138
	v_cmp_gt_f32_e32 vcc, s9, v138
	v_pk_mul_f32 v[106:107], v[106:107], v[42:43]
	v_pk_mul_f32 v[104:105], v[104:105], v[40:41]
	v_cndmask_b32_e32 v138, v138, v139, vcc
	v_rsq_f32_e32 v138, v138
	v_pk_mul_f32 v[110:111], v[110:111], v[46:47]
	v_pk_mul_f32 v[108:109], v[108:109], v[44:45]
	v_mul_f32_e32 v139, 0x45800000, v138
	v_cndmask_b32_e32 v140, v138, v139, vcc
	v_pk_mul_f32 v[114:115], v[114:115], v[50:51]
	v_pk_mul_f32 v[112:113], v[112:113], v[48:49]
	v_pk_mul_f32 v[118:119], v[118:119], v[54:55]
	v_pk_mul_f32 v[116:117], v[116:117], v[52:53]
	v_pk_mul_f32 v[122:123], v[122:123], v[58:59]
	v_pk_mul_f32 v[120:121], v[120:121], v[56:57]
	v_pk_mul_f32 v[126:127], v[126:127], v[62:63]
	v_pk_mul_f32 v[124:125], v[124:125], v[60:61]
	v_pk_mul_f32 v[130:131], v[130:131], v[66:67]
	v_pk_mul_f32 v[128:129], v[128:129], v[64:65]
	v_pk_mul_f32 v[134:135], v[134:135], v[70:71]
	v_pk_mul_f32 v[132:133], v[132:133], v[68:69]
	v_pk_mul_f32 v[106:107], v[106:107], v[140:141] op_sel_hi:[1,0]
	v_pk_mul_f32 v[104:105], v[104:105], v[140:141] op_sel_hi:[1,0]
	v_pk_mul_f32 v[110:111], v[110:111], v[140:141] op_sel_hi:[1,0]
	v_pk_mul_f32 v[108:109], v[108:109], v[140:141] op_sel_hi:[1,0]
	v_pk_mul_f32 v[114:115], v[114:115], v[140:141] op_sel_hi:[1,0]
	v_pk_mul_f32 v[112:113], v[112:113], v[140:141] op_sel_hi:[1,0]
	v_pk_mul_f32 v[118:119], v[118:119], v[140:141] op_sel_hi:[1,0]
	v_pk_mul_f32 v[116:117], v[116:117], v[140:141] op_sel_hi:[1,0]
	v_pk_mul_f32 v[122:123], v[122:123], v[140:141] op_sel_hi:[1,0]
	v_pk_mul_f32 v[120:121], v[120:121], v[140:141] op_sel_hi:[1,0]
	v_pk_mul_f32 v[126:127], v[126:127], v[140:141] op_sel_hi:[1,0]
	v_pk_mul_f32 v[124:125], v[124:125], v[140:141] op_sel_hi:[1,0]
	v_pk_mul_f32 v[130:131], v[130:131], v[140:141] op_sel_hi:[1,0]
	v_pk_mul_f32 v[128:129], v[128:129], v[140:141] op_sel_hi:[1,0]
	v_pk_mul_f32 v[134:135], v[134:135], v[140:141] op_sel_hi:[1,0]
	v_pk_mul_f32 v[132:133], v[132:133], v[140:141] op_sel_hi:[1,0]
	global_store_dwordx4 v0, v[104:107], s[16:17]
	global_store_dwordx4 v0, v[108:111], s[16:17] offset:1024
	global_store_dwordx4 v0, v[112:115], s[16:17] offset:2048
	global_store_dwordx4 v0, v[116:119], s[16:17] offset:3072
	global_store_dwordx4 v0, v[120:123], s[18:19]
	global_store_dwordx4 v0, v[124:127], s[18:19] offset:1024
	global_store_dwordx4 v0, v[128:131], s[18:19] offset:2048
	global_store_dwordx4 v0, v[132:135], s[18:19] offset:3072
